# conv LayerNorm wave reductions via DPP + permlane swaps instead of ds_bpermute; conv item slots rotated; attention K/V prefetch + exp interleave
# speedup vs baseline: 1.0200x; 1.0200x over previous
; __global__ void __launch_bounds__(512, 2) fwd_kernel(Params p) {
;     ...
;             if (G == 256) {
;                 const int sidx = cu < 64 ? cu : (cu >= 192 ? cu - 128 : -1);
;                 if (sidx >= 0) for (int it = sidx; it < n_conv; it += 128) conv_item(p, lds, l, it, UC, MIXA);
.LBB0_749:
	s_andn2_b64 vcc, exec, s[0:1]
	s_cbranch_vccnz .LBB0_751
	v_readlane_b32 s8, v255, 17
	s_add_u32 s101, s8, 32
	s_and_b32 s101, s101, 0x7f
	s_cmp_lt_u32 s8, 0x80
	s_cselect_b32 s8, s101, s8
	s_lshl_b32 s7, s8, 6
	s_cmp_ge_u32 s8, s4
	s_cbranch_scc0 .LBB0_768

; #define LAS __attribute__((address_space(3)))
; __device__ __forceinline__ void conv_item(const Params& p, LAS unsigned char* lds, int l, int item, const bf16_t* UC, bf16_t* MIXA) {
;     ...
;     const int ts = t0 + th * 32;
;     float w[31];
; #pragma unroll
;     for (int k = 0; k < 31; ++k) w[k] = p.conv_w[(size_t)l * 31 * 256 + k * 256 + ch];
;     float o[32];
;     const float bias = p.conv_b[l * 256 + ch];
;     const LAS float* zp = zl + (th * 32) * 256 + ch;
;     float z[62];
; #pragma unroll
;     for (int jj = 0; jj < 62; ++jj) z[jj] = zp[jj * 256];
.LBB0_767:
	s_or_b64 exec, exec, s[0:1]
	v_readlane_b32 s52, v252, 32
	s_waitcnt vmcnt(0)
	v_ashrrev_i32_e32 v0, 3, v61
	v_or_b32_sdwa v160, v61, s5 dst_sel:DWORD dst_unused:UNUSED_PAD src0_sel:BYTE_0 src1_sel:DWORD
	v_readlane_b32 s66, v252, 46
	v_readlane_b32 s67, v252, 47
	v_and_b32_e32 v66, 0xffffffe0, v0
	s_waitcnt lgkmcnt(0)
	v_lshl_add_u64 v[0:1], v[160:161], 2, s[66:67]
	v_add_co_u32_e32 v2, vcc, 0x1000, v0
	s_barrier
	s_nop 0
	v_addc_co_u32_e32 v3, vcc, 0, v1, vcc
	global_load_dword v67, v[0:1], off
	global_load_dword v68, v[0:1], off offset:1024
	global_load_dword v69, v[0:1], off offset:2048
	global_load_dword v70, v[0:1], off offset:3072
	global_load_dword v72, v[2:3], off
	global_load_dword v73, v[2:3], off offset:1024
	global_load_dword v74, v[2:3], off offset:2048
	global_load_dword v75, v[2:3], off offset:3072
	v_add_co_u32_e32 v2, vcc, s21, v0
	s_movk_i32 s0, 0x3000
	s_nop 0
	v_addc_co_u32_e32 v3, vcc, 0, v1, vcc
	v_add_co_u32_e32 v4, vcc, s0, v0
	s_movk_i32 s0, 0x4000
	s_nop 0
	v_addc_co_u32_e32 v5, vcc, 0, v1, vcc
	global_load_dword v76, v[4:5], off offset:-4096
	global_load_dword v77, v[2:3], off offset:1024
	global_load_dword v78, v[2:3], off offset:2048
	global_load_dword v79, v[2:3], off offset:3072
	global_load_dword v80, v[4:5], off
	global_load_dword v81, v[4:5], off offset:1024
	global_load_dword v82, v[4:5], off offset:2048
	global_load_dword v83, v[4:5], off offset:3072
	v_add_co_u32_e32 v2, vcc, s0, v0
	s_movk_i32 s0, 0x5000
	s_nop 0
	v_addc_co_u32_e32 v3, vcc, 0, v1, vcc
	v_add_co_u32_e32 v4, vcc, s0, v0
	s_movk_i32 s0, 0x6000
	s_nop 0
	v_addc_co_u32_e32 v5, vcc, 0, v1, vcc
	global_load_dword v84, v[4:5], off offset:-4096
	global_load_dword v85, v[2:3], off offset:1024
	global_load_dword v86, v[2:3], off offset:2048
	global_load_dword v87, v[2:3], off offset:3072
	global_load_dword v88, v[4:5], off
	global_load_dword v89, v[4:5], off offset:1024
	global_load_dword v90, v[4:5], off offset:2048
	global_load_dword v91, v[4:5], off offset:3072
	v_add_co_u32_e32 v2, vcc, s0, v0
	s_movk_i32 s0, 0x7000
	s_nop 0
	v_addc_co_u32_e32 v3, vcc, 0, v1, vcc
	v_readlane_b32 s53, v252, 33
	v_readlane_b32 s54, v252, 34
	v_readlane_b32 s55, v252, 35
	v_readlane_b32 s56, v252, 36
	v_readlane_b32 s57, v252, 37
	v_readlane_b32 s58, v252, 38
	v_readlane_b32 s59, v252, 39
	v_readlane_b32 s60, v252, 40
	v_readlane_b32 s61, v252, 41
	v_readlane_b32 s62, v252, 42
	v_readlane_b32 s63, v252, 43
	v_readlane_b32 s64, v252, 44
	v_readlane_b32 s65, v252, 45
	v_add_co_u32_e32 v0, vcc, s0, v0
	v_or_b32_sdwa v160, v61, s6 dst_sel:DWORD dst_unused:UNUSED_PAD src0_sel:BYTE_0 src1_sel:DWORD
	s_nop 0
	v_addc_co_u32_e32 v1, vcc, 0, v1, vcc
	v_readlane_b32 s52, v252, 48
	global_load_dword v92, v[0:1], off offset:-4096
	global_load_dword v93, v[2:3], off offset:1024
	global_load_dword v94, v[2:3], off offset:2048
	global_load_dword v95, v[2:3], off offset:3072
	global_load_dword v96, v[0:1], off
	global_load_dword v97, v[0:1], off offset:1024
	global_load_dword v98, v[0:1], off offset:2048
	v_lshlrev_b64 v[0:1], 2, v[160:161]
	v_readlane_b32 s53, v252, 49
	v_readlane_b32 s54, v252, 50
	v_readlane_b32 s55, v252, 51
	v_lshl_add_u64 v[2:3], s[52:53], 0, v[0:1]
	global_load_dword v60, v[2:3], off
	v_lshlrev_b32_e32 v2, 10, v66
	v_lshlrev_b32_sdwa v3, v208, v61 dst_sel:DWORD dst_unused:UNUSED_PAD src0_sel:DWORD src1_sel:BYTE_0
	v_add3_u32 v2, 0, v2, v3
	ds_read2st64_b32 v[62:63], v2 offset1:4
	ds_read2st64_b32 v[100:101], v2 offset0:8 offset1:12
	ds_read2st64_b32 v[58:59], v2 offset0:16 offset1:20
	ds_read2st64_b32 v[56:57], v2 offset0:24 offset1:28
	ds_read2st64_b32 v[54:55], v2 offset0:32 offset1:36
	ds_read2st64_b32 v[52:53], v2 offset0:40 offset1:44
	ds_read2st64_b32 v[50:51], v2 offset0:48 offset1:52
	ds_read2st64_b32 v[48:49], v2 offset0:56 offset1:60
	ds_read2st64_b32 v[46:47], v2 offset0:64 offset1:68
	ds_read2st64_b32 v[44:45], v2 offset0:72 offset1:76
	ds_read2st64_b32 v[42:43], v2 offset0:80 offset1:84
	ds_read2st64_b32 v[40:41], v2 offset0:88 offset1:92
	ds_read2st64_b32 v[38:39], v2 offset0:96 offset1:100
	ds_read2st64_b32 v[36:37], v2 offset0:104 offset1:108
	ds_read2st64_b32 v[34:35], v2 offset0:112 offset1:116
	ds_read2st64_b32 v[32:33], v2 offset0:120 offset1:124
	ds_read2st64_b32 v[30:31], v2 offset0:128 offset1:132
	ds_read2st64_b32 v[28:29], v2 offset0:136 offset1:140
	ds_read2st64_b32 v[26:27], v2 offset0:144 offset1:148
	ds_read2st64_b32 v[24:25], v2 offset0:152 offset1:156
	ds_read2st64_b32 v[22:23], v2 offset0:160 offset1:164
	ds_read2st64_b32 v[20:21], v2 offset0:168 offset1:172
	ds_read2st64_b32 v[18:19], v2 offset0:176 offset1:180
	ds_read2st64_b32 v[16:17], v2 offset0:184 offset1:188
	ds_read2st64_b32 v[14:15], v2 offset0:192 offset1:196
	ds_read2st64_b32 v[12:13], v2 offset0:200 offset1:204
	ds_read2st64_b32 v[10:11], v2 offset0:208 offset1:212
	ds_read2st64_b32 v[8:9], v2 offset0:216 offset1:220
	ds_read2st64_b32 v[6:7], v2 offset0:224 offset1:228
	ds_read2st64_b32 v[4:5], v2 offset0:232 offset1:236
	ds_read2st64_b32 v[2:3], v2 offset0:240 offset1:244
	v_readlane_b32 s56, v252, 52
	v_readlane_b32 s57, v252, 53
	s_add_i32 s9, s9, s10
	v_readlane_b32 s0, v253, 16
	v_lshlrev_b32_sdwa v160, v196, v61 dst_sel:DWORD dst_unused:UNUSED_PAD src0_sel:DWORD src1_sel:BYTE_0
	v_readlane_b32 s1, v253, 17
	s_addk_i32 s8, 0x80
	s_addk_i32 s7, 0x2000
	s_cmp_ge_i32 s8, s4
	v_readlane_b32 s58, v252, 54
	v_readlane_b32 s59, v252, 55
	v_readlane_b32 s60, v252, 56
	v_readlane_b32 s61, v252, 57
	v_readlane_b32 s62, v252, 58
	v_readlane_b32 s63, v252, 59
	v_readlane_b32 s64, v252, 60
	v_readlane_b32 s65, v252, 61
	v_readlane_b32 s66, v252, 62
	v_readlane_b32 s67, v252, 63
	s_waitcnt vmcnt(0) lgkmcnt(14)
; __device__ __forceinline__ void conv_item(const Params& p, LAS unsigned char* lds, int l, int item, const bf16_t* UC, bf16_t* MIXA) {
;     ...
; #pragma unroll
;     for (int i = 0; i < 32; ++i) {
;         float acc = bias;
; #pragma unroll
;         for (int k = 0; k < 31; ++k) acc += w[k] * z[i + k];
;         o[i] = acc;
;     }
	v_fma_f32 v71, v67, v62, v60
	v_fmac_f32_e32 v71, v68, v63
	v_fma_f32 v65, v67, v63, v60
	v_fmac_f32_e32 v71, v69, v100
	v_fmac_f32_e32 v65, v68, v100
	v_fma_f32 v64, v67, v100, v60
	v_fmac_f32_e32 v71, v70, v101
	v_fmac_f32_e32 v65, v69, v101
	v_fmac_f32_e32 v64, v68, v101
	v_fma_f32 v63, v67, v101, v60
	v_fmac_f32_e32 v71, v72, v58
	v_fmac_f32_e32 v65, v70, v58
	v_fmac_f32_e32 v64, v69, v58
	v_fmac_f32_e32 v63, v68, v58
	v_fma_f32 v62, v67, v58, v60
	v_fmac_f32_e32 v71, v73, v59
	v_fmac_f32_e32 v65, v72, v59
	v_fmac_f32_e32 v64, v70, v59
	v_fmac_f32_e32 v63, v69, v59
	v_fmac_f32_e32 v62, v68, v59
	v_fma_f32 v59, v67, v59, v60
	v_fmac_f32_e32 v71, v74, v56
	v_fmac_f32_e32 v65, v73, v56
	v_fmac_f32_e32 v64, v72, v56
	v_fmac_f32_e32 v63, v70, v56
	v_fmac_f32_e32 v62, v69, v56
	v_fmac_f32_e32 v59, v68, v56
	v_fma_f32 v58, v67, v56, v60
	v_fmac_f32_e32 v71, v75, v57
	v_fmac_f32_e32 v65, v74, v57
	v_fmac_f32_e32 v64, v73, v57
	v_fmac_f32_e32 v63, v72, v57
	v_fmac_f32_e32 v62, v70, v57
	v_fmac_f32_e32 v59, v69, v57
	v_fmac_f32_e32 v58, v68, v57
	v_fma_f32 v57, v67, v57, v60
	v_fmac_f32_e32 v71, v76, v54
	v_fmac_f32_e32 v65, v75, v54
	v_fmac_f32_e32 v64, v74, v54
	v_fmac_f32_e32 v63, v73, v54
	v_fmac_f32_e32 v62, v72, v54
	v_fmac_f32_e32 v59, v70, v54
	v_fmac_f32_e32 v58, v69, v54
	v_fmac_f32_e32 v57, v68, v54
	v_fma_f32 v56, v67, v54, v60
	v_fmac_f32_e32 v71, v77, v55
	v_fmac_f32_e32 v65, v76, v55
	v_fmac_f32_e32 v64, v75, v55
	v_fmac_f32_e32 v63, v74, v55
	v_fmac_f32_e32 v62, v73, v55
	v_fmac_f32_e32 v59, v72, v55
	v_fmac_f32_e32 v58, v70, v55
	v_fmac_f32_e32 v57, v69, v55
	v_fmac_f32_e32 v56, v68, v55
	v_fma_f32 v55, v67, v55, v60
	v_fmac_f32_e32 v71, v78, v52
	v_fmac_f32_e32 v65, v77, v52
	v_fmac_f32_e32 v64, v76, v52
	v_fmac_f32_e32 v63, v75, v52
	v_fmac_f32_e32 v62, v74, v52
	v_fmac_f32_e32 v59, v73, v52
	v_fmac_f32_e32 v58, v72, v52
	v_fmac_f32_e32 v57, v70, v52
	v_fmac_f32_e32 v56, v69, v52
	v_fmac_f32_e32 v55, v68, v52
	v_fma_f32 v54, v67, v52, v60
	v_fmac_f32_e32 v71, v79, v53
	v_fmac_f32_e32 v65, v78, v53
	v_fmac_f32_e32 v64, v77, v53
	v_fmac_f32_e32 v63, v76, v53
	v_fmac_f32_e32 v62, v75, v53
	v_fmac_f32_e32 v59, v74, v53
	v_fmac_f32_e32 v58, v73, v53
	v_fmac_f32_e32 v57, v72, v53
	v_fmac_f32_e32 v56, v70, v53
	v_fmac_f32_e32 v55, v69, v53
	v_fmac_f32_e32 v54, v68, v53
	v_fma_f32 v53, v67, v53, v60
	v_fmac_f32_e32 v71, v80, v50
	v_fmac_f32_e32 v65, v79, v50
	v_fmac_f32_e32 v64, v78, v50
	v_fmac_f32_e32 v63, v77, v50
	v_fmac_f32_e32 v62, v76, v50
	v_fmac_f32_e32 v59, v75, v50
	v_fmac_f32_e32 v58, v74, v50
	v_fmac_f32_e32 v57, v73, v50
	v_fmac_f32_e32 v56, v72, v50
	v_fmac_f32_e32 v55, v70, v50
	v_fmac_f32_e32 v54, v69, v50
	v_fmac_f32_e32 v53, v68, v50
	v_fma_f32 v52, v67, v50, v60
	v_fmac_f32_e32 v71, v81, v51
	v_fmac_f32_e32 v65, v80, v51
	v_fmac_f32_e32 v64, v79, v51
	v_fmac_f32_e32 v63, v78, v51
	v_fmac_f32_e32 v62, v77, v51
	v_fmac_f32_e32 v59, v76, v51
	v_fmac_f32_e32 v58, v75, v51
	v_fmac_f32_e32 v57, v74, v51
	v_fmac_f32_e32 v56, v73, v51
	v_fmac_f32_e32 v55, v72, v51
	v_fmac_f32_e32 v54, v70, v51
	v_fmac_f32_e32 v53, v69, v51
	v_fmac_f32_e32 v52, v68, v51
	v_fma_f32 v51, v67, v51, v60
	v_fmac_f32_e32 v71, v82, v48
	v_fmac_f32_e32 v65, v81, v48
	v_fmac_f32_e32 v64, v80, v48
	v_fmac_f32_e32 v63, v79, v48
	v_fmac_f32_e32 v62, v78, v48
	v_fmac_f32_e32 v59, v77, v48
	v_fmac_f32_e32 v58, v76, v48
	v_fmac_f32_e32 v57, v75, v48
	v_fmac_f32_e32 v56, v74, v48
	v_fmac_f32_e32 v55, v73, v48
	v_fmac_f32_e32 v54, v72, v48
	v_fmac_f32_e32 v53, v70, v48
	v_fmac_f32_e32 v52, v69, v48
	v_fmac_f32_e32 v51, v68, v48
	v_fma_f32 v50, v67, v48, v60
	v_fmac_f32_e32 v71, v83, v49
	v_fmac_f32_e32 v65, v82, v49
	v_fmac_f32_e32 v64, v81, v49
	v_fmac_f32_e32 v63, v80, v49
	v_fmac_f32_e32 v62, v79, v49
	v_fmac_f32_e32 v59, v78, v49
	v_fmac_f32_e32 v58, v77, v49
	v_fmac_f32_e32 v57, v76, v49
	v_fmac_f32_e32 v56, v75, v49
	v_fmac_f32_e32 v55, v74, v49
	v_fmac_f32_e32 v54, v73, v49
	v_fmac_f32_e32 v53, v72, v49
	v_fmac_f32_e32 v52, v70, v49
	v_fmac_f32_e32 v51, v69, v49
	v_fmac_f32_e32 v50, v68, v49
	v_fma_f32 v49, v67, v49, v60
	v_fmac_f32_e32 v71, v84, v46
	v_fmac_f32_e32 v65, v83, v46
	v_fmac_f32_e32 v64, v82, v46
	v_fmac_f32_e32 v63, v81, v46
	v_fmac_f32_e32 v62, v80, v46
	v_fmac_f32_e32 v59, v79, v46
	v_fmac_f32_e32 v58, v78, v46
	v_fmac_f32_e32 v57, v77, v46
	v_fmac_f32_e32 v56, v76, v46
	v_fmac_f32_e32 v55, v75, v46
	v_fmac_f32_e32 v54, v74, v46
	v_fmac_f32_e32 v53, v73, v46
	v_fmac_f32_e32 v52, v72, v46
	v_fmac_f32_e32 v51, v70, v46
	v_fmac_f32_e32 v50, v69, v46
	v_fmac_f32_e32 v49, v68, v46
	v_fma_f32 v48, v67, v46, v60
	v_fmac_f32_e32 v71, v85, v47
	v_fmac_f32_e32 v65, v84, v47
	v_fmac_f32_e32 v64, v83, v47
	v_fmac_f32_e32 v63, v82, v47
	v_fmac_f32_e32 v62, v81, v47
	v_fmac_f32_e32 v59, v80, v47
	v_fmac_f32_e32 v58, v79, v47
	v_fmac_f32_e32 v57, v78, v47
	v_fmac_f32_e32 v56, v77, v47
	v_fmac_f32_e32 v55, v76, v47
	v_fmac_f32_e32 v54, v75, v47
	v_fmac_f32_e32 v53, v74, v47
	v_fmac_f32_e32 v52, v73, v47
	v_fmac_f32_e32 v51, v72, v47
	v_fmac_f32_e32 v50, v70, v47
	v_fmac_f32_e32 v49, v69, v47
	v_fmac_f32_e32 v48, v68, v47
	v_fma_f32 v47, v67, v47, v60
	v_fmac_f32_e32 v71, v86, v44
	v_fmac_f32_e32 v65, v85, v44
	v_fmac_f32_e32 v64, v84, v44
	v_fmac_f32_e32 v63, v83, v44
	v_fmac_f32_e32 v62, v82, v44
	v_fmac_f32_e32 v59, v81, v44
	v_fmac_f32_e32 v58, v80, v44
	v_fmac_f32_e32 v57, v79, v44
	v_fmac_f32_e32 v56, v78, v44
	v_fmac_f32_e32 v55, v77, v44
	v_fmac_f32_e32 v54, v76, v44
	v_fmac_f32_e32 v53, v75, v44
	v_fmac_f32_e32 v52, v74, v44
	v_fmac_f32_e32 v51, v73, v44
	v_fmac_f32_e32 v50, v72, v44
	v_fmac_f32_e32 v49, v70, v44
	v_fmac_f32_e32 v48, v69, v44
; __device__ __forceinline__ void conv_item(const Params& p, LAS unsigned char* lds, int l, int item, const bf16_t* UC, bf16_t* MIXA) {
;     ...
; #pragma unroll
;     for (int i = 0; i < 32; ++i) {
;         float acc = bias;
; #pragma unroll
;         for (int k = 0; k < 31; ++k) acc += w[k] * z[i + k];
;         o[i] = acc;
;     }
	v_fmac_f32_e32 v47, v68, v44
	v_fma_f32 v46, v67, v44, v60
	v_fmac_f32_e32 v71, v87, v45
	v_fmac_f32_e32 v65, v86, v45
	v_fmac_f32_e32 v64, v85, v45
	v_fmac_f32_e32 v63, v84, v45
	v_fmac_f32_e32 v62, v83, v45
	v_fmac_f32_e32 v59, v82, v45
	v_fmac_f32_e32 v58, v81, v45
	v_fmac_f32_e32 v57, v80, v45
	v_fmac_f32_e32 v56, v79, v45
	v_fmac_f32_e32 v55, v78, v45
	v_fmac_f32_e32 v54, v77, v45
	v_fmac_f32_e32 v53, v76, v45
	v_fmac_f32_e32 v52, v75, v45
	v_fmac_f32_e32 v51, v74, v45
	v_fmac_f32_e32 v50, v73, v45
	v_fmac_f32_e32 v49, v72, v45
	v_fmac_f32_e32 v48, v70, v45
	v_fmac_f32_e32 v47, v69, v45
	v_fmac_f32_e32 v46, v68, v45
	v_fma_f32 v45, v67, v45, v60
	v_fmac_f32_e32 v71, v88, v42
	v_fmac_f32_e32 v65, v87, v42
	v_fmac_f32_e32 v64, v86, v42
	v_fmac_f32_e32 v63, v85, v42
	v_fmac_f32_e32 v62, v84, v42
	v_fmac_f32_e32 v59, v83, v42
	v_fmac_f32_e32 v58, v82, v42
	v_fmac_f32_e32 v57, v81, v42
	v_fmac_f32_e32 v56, v80, v42
	v_fmac_f32_e32 v55, v79, v42
	v_fmac_f32_e32 v54, v78, v42
	v_fmac_f32_e32 v53, v77, v42
	v_fmac_f32_e32 v52, v76, v42
	v_fmac_f32_e32 v51, v75, v42
	v_fmac_f32_e32 v50, v74, v42
	v_fmac_f32_e32 v49, v73, v42
	v_fmac_f32_e32 v48, v72, v42
	v_fmac_f32_e32 v47, v70, v42
	v_fmac_f32_e32 v46, v69, v42
	v_fmac_f32_e32 v45, v68, v42
	v_fma_f32 v44, v67, v42, v60
	v_fmac_f32_e32 v71, v89, v43
	v_fmac_f32_e32 v65, v88, v43
	v_fmac_f32_e32 v64, v87, v43
	v_fmac_f32_e32 v63, v86, v43
	v_fmac_f32_e32 v62, v85, v43
	v_fmac_f32_e32 v59, v84, v43
	v_fmac_f32_e32 v58, v83, v43
	v_fmac_f32_e32 v57, v82, v43
	v_fmac_f32_e32 v56, v81, v43
	v_fmac_f32_e32 v55, v80, v43
	v_fmac_f32_e32 v54, v79, v43
	v_fmac_f32_e32 v53, v78, v43
	v_fmac_f32_e32 v52, v77, v43
	v_fmac_f32_e32 v51, v76, v43
	v_fmac_f32_e32 v50, v75, v43
	v_fmac_f32_e32 v49, v74, v43
	v_fmac_f32_e32 v48, v73, v43
	v_fmac_f32_e32 v47, v72, v43
	v_fmac_f32_e32 v46, v70, v43
	v_fmac_f32_e32 v45, v69, v43
	v_fmac_f32_e32 v44, v68, v43
	v_fma_f32 v43, v67, v43, v60
	v_fmac_f32_e32 v71, v90, v40
	v_fmac_f32_e32 v65, v89, v40
	v_fmac_f32_e32 v64, v88, v40
	v_fmac_f32_e32 v63, v87, v40
	v_fmac_f32_e32 v62, v86, v40
	v_fmac_f32_e32 v59, v85, v40
	v_fmac_f32_e32 v58, v84, v40
	v_fmac_f32_e32 v57, v83, v40
	v_fmac_f32_e32 v56, v82, v40
	v_fmac_f32_e32 v55, v81, v40
	v_fmac_f32_e32 v54, v80, v40
	v_fmac_f32_e32 v53, v79, v40
	v_fmac_f32_e32 v52, v78, v40
	v_fmac_f32_e32 v51, v77, v40
	v_fmac_f32_e32 v50, v76, v40
	v_fmac_f32_e32 v49, v75, v40
	v_fmac_f32_e32 v48, v74, v40
	v_fmac_f32_e32 v47, v73, v40
	v_fmac_f32_e32 v46, v72, v40
	v_fmac_f32_e32 v45, v70, v40
	v_fmac_f32_e32 v44, v69, v40
	v_fmac_f32_e32 v43, v68, v40
	v_fma_f32 v42, v67, v40, v60
	v_fmac_f32_e32 v71, v91, v41
	v_fmac_f32_e32 v65, v90, v41
	v_fmac_f32_e32 v64, v89, v41
	v_fmac_f32_e32 v63, v88, v41
	v_fmac_f32_e32 v62, v87, v41
	v_fmac_f32_e32 v59, v86, v41
	v_fmac_f32_e32 v58, v85, v41
	v_fmac_f32_e32 v57, v84, v41
	v_fmac_f32_e32 v56, v83, v41
	v_fmac_f32_e32 v55, v82, v41
	v_fmac_f32_e32 v54, v81, v41
	v_fmac_f32_e32 v53, v80, v41
	v_fmac_f32_e32 v52, v79, v41
	v_fmac_f32_e32 v51, v78, v41
	v_fmac_f32_e32 v50, v77, v41
	v_fmac_f32_e32 v49, v76, v41
	v_fmac_f32_e32 v48, v75, v41
	v_fmac_f32_e32 v47, v74, v41
	v_fmac_f32_e32 v46, v73, v41
	v_fmac_f32_e32 v45, v72, v41
	v_fmac_f32_e32 v44, v70, v41
	v_fmac_f32_e32 v43, v69, v41
	v_fmac_f32_e32 v42, v68, v41
	v_fma_f32 v41, v67, v41, v60
	v_fmac_f32_e32 v71, v92, v38
	v_fmac_f32_e32 v65, v91, v38
	v_fmac_f32_e32 v64, v90, v38
	v_fmac_f32_e32 v63, v89, v38
	v_fmac_f32_e32 v62, v88, v38
	v_fmac_f32_e32 v59, v87, v38
	v_fmac_f32_e32 v58, v86, v38
	v_fmac_f32_e32 v57, v85, v38
	v_fmac_f32_e32 v56, v84, v38
	v_fmac_f32_e32 v55, v83, v38
	v_fmac_f32_e32 v54, v82, v38
	v_fmac_f32_e32 v53, v81, v38
	v_fmac_f32_e32 v52, v80, v38
	v_fmac_f32_e32 v51, v79, v38
	v_fmac_f32_e32 v50, v78, v38
	v_fmac_f32_e32 v49, v77, v38
	v_fmac_f32_e32 v48, v76, v38
	v_fmac_f32_e32 v47, v75, v38
	v_fmac_f32_e32 v46, v74, v38
	v_fmac_f32_e32 v45, v73, v38
	v_fmac_f32_e32 v44, v72, v38
	v_fmac_f32_e32 v43, v70, v38
	v_fmac_f32_e32 v42, v69, v38
	v_fmac_f32_e32 v41, v68, v38
	v_fma_f32 v40, v67, v38, v60
	v_fmac_f32_e32 v71, v93, v39
	v_fmac_f32_e32 v65, v92, v39
	v_fmac_f32_e32 v64, v91, v39
	v_fmac_f32_e32 v63, v90, v39
	v_fmac_f32_e32 v62, v89, v39
	v_fmac_f32_e32 v59, v88, v39
	v_fmac_f32_e32 v58, v87, v39
	v_fmac_f32_e32 v57, v86, v39
	v_fmac_f32_e32 v56, v85, v39
	v_fmac_f32_e32 v55, v84, v39
	v_fmac_f32_e32 v54, v83, v39
	v_fmac_f32_e32 v53, v82, v39
	v_fmac_f32_e32 v52, v81, v39
	v_fmac_f32_e32 v51, v80, v39
	v_fmac_f32_e32 v50, v79, v39
	v_fmac_f32_e32 v49, v78, v39
	v_fmac_f32_e32 v48, v77, v39
	v_fmac_f32_e32 v47, v76, v39
	v_fmac_f32_e32 v46, v75, v39
	v_fmac_f32_e32 v45, v74, v39
	v_fmac_f32_e32 v44, v73, v39
	v_fmac_f32_e32 v43, v72, v39
	v_fmac_f32_e32 v42, v70, v39
	v_fmac_f32_e32 v41, v69, v39
	v_fmac_f32_e32 v40, v68, v39
	v_fma_f32 v39, v67, v39, v60
	v_fmac_f32_e32 v71, v94, v36
	v_fmac_f32_e32 v65, v93, v36
	v_fmac_f32_e32 v64, v92, v36
	v_fmac_f32_e32 v63, v91, v36
	v_fmac_f32_e32 v62, v90, v36
	v_fmac_f32_e32 v59, v89, v36
	v_fmac_f32_e32 v58, v88, v36
	v_fmac_f32_e32 v57, v87, v36
	v_fmac_f32_e32 v56, v86, v36
	v_fmac_f32_e32 v55, v85, v36
	v_fmac_f32_e32 v54, v84, v36
	v_fmac_f32_e32 v53, v83, v36
	v_fmac_f32_e32 v52, v82, v36
	v_fmac_f32_e32 v51, v81, v36
	v_fmac_f32_e32 v50, v80, v36
	v_fmac_f32_e32 v49, v79, v36
	v_fmac_f32_e32 v48, v78, v36
	v_fmac_f32_e32 v47, v77, v36
	v_fmac_f32_e32 v46, v76, v36
	v_fmac_f32_e32 v45, v75, v36
	v_fmac_f32_e32 v44, v74, v36
	v_fmac_f32_e32 v43, v73, v36
	v_fmac_f32_e32 v42, v72, v36
	v_fmac_f32_e32 v41, v70, v36
	v_fmac_f32_e32 v40, v69, v36
; __device__ __forceinline__ void conv_item(const Params& p, LAS unsigned char* lds, int l, int item, const bf16_t* UC, bf16_t* MIXA) {
;     ...
; #pragma unroll
;     for (int i = 0; i < 32; ++i) {
;         float acc = bias;
; #pragma unroll
;         for (int k = 0; k < 31; ++k) acc += w[k] * z[i + k];
;         o[i] = acc;
;     }
	v_fmac_f32_e32 v39, v68, v36
	v_fma_f32 v38, v67, v36, v60
	v_fmac_f32_e32 v71, v95, v37
	v_fmac_f32_e32 v65, v94, v37
	v_fmac_f32_e32 v64, v93, v37
	v_fmac_f32_e32 v63, v92, v37
	v_fmac_f32_e32 v62, v91, v37
	v_fmac_f32_e32 v59, v90, v37
	v_fmac_f32_e32 v58, v89, v37
	v_fmac_f32_e32 v57, v88, v37
	v_fmac_f32_e32 v56, v87, v37
	v_fmac_f32_e32 v55, v86, v37
	v_fmac_f32_e32 v54, v85, v37
	v_fmac_f32_e32 v53, v84, v37
	v_fmac_f32_e32 v52, v83, v37
	v_fmac_f32_e32 v51, v82, v37
	v_fmac_f32_e32 v50, v81, v37
	v_fmac_f32_e32 v49, v80, v37
	v_fmac_f32_e32 v48, v79, v37
	v_fmac_f32_e32 v47, v78, v37
	v_fmac_f32_e32 v46, v77, v37
	v_fmac_f32_e32 v45, v76, v37
	v_fmac_f32_e32 v44, v75, v37
	v_fmac_f32_e32 v43, v74, v37
	v_fmac_f32_e32 v42, v73, v37
	v_fmac_f32_e32 v41, v72, v37
	v_fmac_f32_e32 v40, v70, v37
	v_fmac_f32_e32 v39, v69, v37
	v_fmac_f32_e32 v38, v68, v37
	v_fma_f32 v37, v67, v37, v60
	v_fmac_f32_e32 v71, v96, v34
	v_fmac_f32_e32 v65, v95, v34
	v_fmac_f32_e32 v64, v94, v34
	v_fmac_f32_e32 v63, v93, v34
	v_fmac_f32_e32 v62, v92, v34
	v_fmac_f32_e32 v59, v91, v34
	v_fmac_f32_e32 v58, v90, v34
	v_fmac_f32_e32 v57, v89, v34
	v_fmac_f32_e32 v56, v88, v34
	v_fmac_f32_e32 v55, v87, v34
	v_fmac_f32_e32 v54, v86, v34
	v_fmac_f32_e32 v53, v85, v34
	v_fmac_f32_e32 v52, v84, v34
	v_fmac_f32_e32 v51, v83, v34
	v_fmac_f32_e32 v50, v82, v34
	v_fmac_f32_e32 v49, v81, v34
	v_fmac_f32_e32 v48, v80, v34
	v_fmac_f32_e32 v47, v79, v34
	v_fmac_f32_e32 v46, v78, v34
	v_fmac_f32_e32 v45, v77, v34
	v_fmac_f32_e32 v44, v76, v34
	v_fmac_f32_e32 v43, v75, v34
	v_fmac_f32_e32 v42, v74, v34
	v_fmac_f32_e32 v41, v73, v34
	v_fmac_f32_e32 v40, v72, v34
	v_fmac_f32_e32 v39, v70, v34
	v_fmac_f32_e32 v38, v69, v34
	v_fmac_f32_e32 v37, v68, v34
	v_fma_f32 v36, v67, v34, v60
	v_fmac_f32_e32 v71, v97, v35
	v_fmac_f32_e32 v65, v96, v35
	v_fmac_f32_e32 v64, v95, v35
	v_fmac_f32_e32 v63, v94, v35
	v_fmac_f32_e32 v62, v93, v35
	v_fmac_f32_e32 v59, v92, v35
	v_fmac_f32_e32 v58, v91, v35
	v_fmac_f32_e32 v57, v90, v35
	v_fmac_f32_e32 v56, v89, v35
	v_fmac_f32_e32 v55, v88, v35
	v_fmac_f32_e32 v54, v87, v35
	v_fmac_f32_e32 v53, v86, v35
	v_fmac_f32_e32 v52, v85, v35
	v_fmac_f32_e32 v51, v84, v35
	v_fmac_f32_e32 v50, v83, v35
	v_fmac_f32_e32 v49, v82, v35
	v_fmac_f32_e32 v48, v81, v35
	v_fmac_f32_e32 v47, v80, v35
	v_fmac_f32_e32 v46, v79, v35
	v_fmac_f32_e32 v45, v78, v35
	v_fmac_f32_e32 v44, v77, v35
	v_fmac_f32_e32 v43, v76, v35
	v_fmac_f32_e32 v42, v75, v35
	v_fmac_f32_e32 v41, v74, v35
	v_fmac_f32_e32 v40, v73, v35
	v_fmac_f32_e32 v39, v72, v35
	v_fmac_f32_e32 v38, v70, v35
	v_fmac_f32_e32 v37, v69, v35
	v_fmac_f32_e32 v36, v68, v35
	v_fma_f32 v34, v67, v35, v60
	v_fmac_f32_e32 v71, v98, v32
	v_fmac_f32_e32 v65, v97, v32
	v_fmac_f32_e32 v64, v96, v32
	v_fmac_f32_e32 v63, v95, v32
	v_fmac_f32_e32 v62, v94, v32
	v_fmac_f32_e32 v59, v93, v32
	v_fmac_f32_e32 v58, v92, v32
	v_fmac_f32_e32 v57, v91, v32
	v_fmac_f32_e32 v56, v90, v32
	v_fmac_f32_e32 v55, v89, v32
	v_fmac_f32_e32 v54, v88, v32
	v_fmac_f32_e32 v53, v87, v32
	v_fmac_f32_e32 v52, v86, v32
	v_fmac_f32_e32 v51, v85, v32
	v_fmac_f32_e32 v50, v84, v32
	v_fmac_f32_e32 v49, v83, v32
	v_fmac_f32_e32 v48, v82, v32
	v_fmac_f32_e32 v47, v81, v32
	v_fmac_f32_e32 v46, v80, v32
	v_fmac_f32_e32 v45, v79, v32
	v_fmac_f32_e32 v44, v78, v32
	v_fmac_f32_e32 v43, v77, v32
	v_fmac_f32_e32 v42, v76, v32
	v_fmac_f32_e32 v41, v75, v32
	v_fmac_f32_e32 v40, v74, v32
	v_fmac_f32_e32 v39, v73, v32
	v_fmac_f32_e32 v38, v72, v32
	v_fmac_f32_e32 v37, v70, v32
	v_fmac_f32_e32 v36, v69, v32
	v_fmac_f32_e32 v34, v68, v32
	v_fma_f32 v32, v67, v32, v60
	v_fmac_f32_e32 v60, v67, v33
	v_fmac_f32_e32 v32, v68, v33
	v_fmac_f32_e32 v60, v68, v30
	v_fmac_f32_e32 v32, v69, v30
	v_fmac_f32_e32 v60, v69, v31
	v_fmac_f32_e32 v34, v69, v33
	v_fmac_f32_e32 v32, v70, v31
	s_waitcnt lgkmcnt(13)
	v_fmac_f32_e32 v60, v70, v28
	v_fmac_f32_e32 v36, v70, v33
	v_fmac_f32_e32 v34, v70, v30
	v_fmac_f32_e32 v32, v72, v28
	v_fmac_f32_e32 v60, v72, v29
	v_fmac_f32_e32 v36, v72, v30
	v_fmac_f32_e32 v34, v72, v31
	v_fmac_f32_e32 v32, v73, v29
	s_waitcnt lgkmcnt(12)
	v_fmac_f32_e32 v60, v73, v26
	v_fmac_f32_e32 v36, v73, v31
	v_fmac_f32_e32 v34, v73, v28
	v_fmac_f32_e32 v32, v74, v26
	v_fmac_f32_e32 v60, v74, v27
	v_fmac_f32_e32 v36, v74, v28
	v_fmac_f32_e32 v34, v74, v29
	v_fmac_f32_e32 v32, v75, v27
	s_waitcnt lgkmcnt(11)
	v_fmac_f32_e32 v60, v75, v24
	v_fmac_f32_e32 v36, v75, v29
	v_fmac_f32_e32 v34, v75, v26
	v_fmac_f32_e32 v32, v76, v24
	v_fmac_f32_e32 v60, v76, v25
	v_fmac_f32_e32 v36, v76, v26
	v_fmac_f32_e32 v34, v76, v27
	v_fmac_f32_e32 v32, v77, v25
	s_waitcnt lgkmcnt(10)
	v_fmac_f32_e32 v60, v77, v22
	v_fmac_f32_e32 v36, v77, v27
	v_fmac_f32_e32 v34, v77, v24
	v_fmac_f32_e32 v32, v78, v22
	v_fmac_f32_e32 v60, v78, v23
	v_fmac_f32_e32 v36, v78, v24
	v_fmac_f32_e32 v34, v78, v25
	v_fmac_f32_e32 v32, v79, v23
	s_waitcnt lgkmcnt(9)
	v_fmac_f32_e32 v60, v79, v20
	v_fmac_f32_e32 v38, v73, v33
	v_fmac_f32_e32 v37, v72, v33
	v_fmac_f32_e32 v36, v79, v25
	v_fmac_f32_e32 v34, v79, v22
	v_fmac_f32_e32 v32, v80, v20
	v_fmac_f32_e32 v60, v80, v21
	v_fmac_f32_e32 v38, v74, v30
	v_fmac_f32_e32 v37, v73, v30
	v_fmac_f32_e32 v36, v80, v22
	v_fmac_f32_e32 v34, v80, v23
	v_fmac_f32_e32 v32, v81, v21
	s_waitcnt lgkmcnt(8)
	v_fmac_f32_e32 v60, v81, v18
	v_fmac_f32_e32 v38, v75, v31
	v_fmac_f32_e32 v37, v74, v31
	v_fmac_f32_e32 v36, v81, v23
	v_fmac_f32_e32 v34, v81, v20
	v_fmac_f32_e32 v32, v82, v18
	v_fmac_f32_e32 v60, v82, v19
	v_fmac_f32_e32 v38, v76, v28
	v_fmac_f32_e32 v37, v75, v28
	v_fmac_f32_e32 v36, v82, v20
	v_fmac_f32_e32 v34, v82, v21
	v_fmac_f32_e32 v32, v83, v19
	s_waitcnt lgkmcnt(7)
; __device__ __forceinline__ bf16_t f2bf(float v) { return (bf16_t)(cvt_pk_bf16(v, 0.f) & 0xffffu); }
; __device__ __forceinline__ float sigmoidf_(float v) { return __builtin_amdgcn_rcpf(1.f + __expf(-v)); }
; __device__ __forceinline__ float wave_sum(float v) {
; #pragma unroll
;     for (int o = 1; o < 64; o <<= 1) v += __shfl_xor(v, o);
;     return v;
; }
; __device__ __forceinline__ void conv_item(const Params& p, LAS unsigned char* lds, int l, int item, const bf16_t* UC, bf16_t* MIXA) {
;     ...
; #pragma unroll
;     for (int i = 0; i < 32; ++i) {
;         float acc = bias;
; #pragma unroll
;         for (int k = 0; k < 31; ++k) acc += w[k] * z[i + k];
;         o[i] = acc;
;     }
;     const float lg = p.conv_ln_g[l * 256 + ch], lb = p.conv_ln_b[l * 256 + ch];
; #pragma unroll
;     for (int i = 0; i < 32; ++i) {
;         const float mu = wave_sum(o[i]) * (1.f / 64.f);
;         const float d = o[i] - mu;
;         const float var = wave_sum(d * d) * (1.f / 64.f);
;         const float zn = d * __builtin_amdgcn_rsqf(var + EPSV) * lg + lb;
;         MIXA[(size_t)(rowbase + ts + i) * DM + 768 + ch] = f2bf(zn * sigmoidf_(zn));
	v_fmac_f32_e32 v60, v83, v16
	v_fmac_f32_e32 v38, v77, v29
	v_fmac_f32_e32 v37, v76, v29
	v_fmac_f32_e32 v36, v83, v21
	v_fmac_f32_e32 v34, v83, v18
	v_fmac_f32_e32 v32, v84, v16
	v_fmac_f32_e32 v60, v84, v17
	v_fmac_f32_e32 v38, v78, v26
	v_fmac_f32_e32 v37, v77, v26
	v_fmac_f32_e32 v36, v84, v18
	v_fmac_f32_e32 v34, v84, v19
	v_fmac_f32_e32 v32, v85, v17
	s_waitcnt lgkmcnt(6)
	v_fmac_f32_e32 v60, v85, v14
	v_fmac_f32_e32 v38, v79, v27
	v_fmac_f32_e32 v37, v78, v27
	v_fmac_f32_e32 v36, v85, v19
	v_fmac_f32_e32 v34, v85, v16
	v_fmac_f32_e32 v32, v86, v14
	v_fmac_f32_e32 v60, v86, v15
	v_fmac_f32_e32 v38, v80, v24
	v_fmac_f32_e32 v37, v79, v24
	v_fmac_f32_e32 v36, v86, v16
	v_fmac_f32_e32 v34, v86, v17
	v_fmac_f32_e32 v32, v87, v15
	s_waitcnt lgkmcnt(5)
	v_fmac_f32_e32 v60, v87, v12
	v_fmac_f32_e32 v38, v81, v25
	v_fmac_f32_e32 v37, v80, v25
	v_fmac_f32_e32 v36, v87, v17
	v_fmac_f32_e32 v34, v87, v14
	v_fmac_f32_e32 v32, v88, v12
	v_fmac_f32_e32 v60, v88, v13
	v_fmac_f32_e32 v38, v82, v22
	v_fmac_f32_e32 v37, v81, v22
	v_fmac_f32_e32 v36, v88, v14
	v_fmac_f32_e32 v34, v88, v15
	v_fmac_f32_e32 v32, v89, v13
	s_waitcnt lgkmcnt(4)
	v_fmac_f32_e32 v60, v89, v10
	v_fmac_f32_e32 v38, v83, v23
	v_fmac_f32_e32 v37, v82, v23
	v_fmac_f32_e32 v36, v89, v15
	v_fmac_f32_e32 v34, v89, v12
	v_fmac_f32_e32 v32, v90, v10
	v_fmac_f32_e32 v60, v90, v11
	v_fmac_f32_e32 v38, v84, v20
	v_fmac_f32_e32 v37, v83, v20
	v_fmac_f32_e32 v36, v90, v12
	v_fmac_f32_e32 v34, v90, v13
	v_fmac_f32_e32 v32, v91, v11
	s_waitcnt lgkmcnt(3)
	v_fmac_f32_e32 v60, v91, v8
	v_fmac_f32_e32 v38, v85, v21
	v_fmac_f32_e32 v37, v84, v21
	v_fmac_f32_e32 v36, v91, v13
	v_fmac_f32_e32 v34, v91, v10
	v_fmac_f32_e32 v32, v92, v8
	v_fmac_f32_e32 v60, v92, v9
	v_fmac_f32_e32 v38, v86, v18
	v_fmac_f32_e32 v37, v85, v18
	v_fmac_f32_e32 v36, v92, v10
	v_fmac_f32_e32 v34, v92, v11
	v_fmac_f32_e32 v32, v93, v9
	s_waitcnt lgkmcnt(2)
	v_fmac_f32_e32 v60, v93, v6
	v_fmac_f32_e32 v38, v87, v19
	v_fmac_f32_e32 v37, v86, v19
	v_fmac_f32_e32 v36, v93, v11
	v_fmac_f32_e32 v34, v93, v8
	v_fmac_f32_e32 v32, v94, v6
	v_fmac_f32_e32 v60, v94, v7
	v_fmac_f32_e32 v38, v88, v16
	v_fmac_f32_e32 v37, v87, v16
	v_fmac_f32_e32 v36, v94, v8
	v_fmac_f32_e32 v34, v94, v9
	v_fmac_f32_e32 v32, v95, v7
	s_waitcnt lgkmcnt(1)
	v_fmac_f32_e32 v60, v95, v4
	v_fmac_f32_e32 v38, v89, v17
	v_fmac_f32_e32 v37, v88, v17
	v_fmac_f32_e32 v36, v95, v9
	v_fmac_f32_e32 v34, v95, v6
	v_fmac_f32_e32 v32, v96, v4
	v_fmac_f32_e32 v60, v96, v5
	v_fmac_f32_e32 v38, v90, v14
	v_fmac_f32_e32 v37, v89, v14
	v_fmac_f32_e32 v36, v96, v6
	v_fmac_f32_e32 v34, v96, v7
	v_fmac_f32_e32 v32, v97, v5
	s_waitcnt lgkmcnt(0)
	v_fmac_f32_e32 v60, v97, v2
	v_fmac_f32_e32 v38, v91, v15
	v_fmac_f32_e32 v37, v90, v15
	v_fmac_f32_e32 v36, v97, v7
	v_fmac_f32_e32 v34, v97, v4
	v_fmac_f32_e32 v32, v98, v2
	v_fmac_f32_e32 v60, v98, v3
	v_lshl_add_u64 v[2:3], s[54:55], 0, v[0:1]
	v_lshl_add_u64 v[0:1], s[56:57], 0, v[0:1]
	v_fmac_f32_e32 v38, v92, v12
	v_fmac_f32_e32 v37, v91, v12
	v_fmac_f32_e32 v36, v98, v4
	v_fmac_f32_e32 v34, v98, v5
	global_load_dword v5, v[2:3], off
	global_load_dword v4, v[0:1], off
	s_nop 1
	v_fmac_f32_e32 v38, v93, v13
	v_fmac_f32_e32 v37, v92, v13
	v_fmac_f32_e32 v38, v94, v10
	v_fmac_f32_e32 v37, v93, v10
	v_fmac_f32_e32 v38, v95, v11
	v_fmac_f32_e32 v37, v94, v11
	v_fmac_f32_e32 v38, v96, v8
	v_fmac_f32_e32 v37, v95, v8
	v_fmac_f32_e32 v38, v97, v9
	v_fmac_f32_e32 v37, v96, v9
	s_waitcnt lgkmcnt(0)
	v_add_f32_dpp v3, v71, v71 quad_perm:[1,0,3,2] row_mask:0xf bank_mask:0xf
	v_fmac_f32_e32 v38, v98, v6
	v_fmac_f32_e32 v37, v97, v6
	s_nop 1
	v_fmac_f32_e32 v40, v75, v33
	v_fmac_f32_e32 v39, v74, v33
	v_fmac_f32_e32 v40, v76, v30
	v_fmac_f32_e32 v39, v75, v30
	s_waitcnt lgkmcnt(0)
	v_add_f32_dpp v3, v3, v3 quad_perm:[2,3,0,1] row_mask:0xf bank_mask:0xf
	s_nop 1
	v_fmac_f32_e32 v40, v77, v31
	v_fmac_f32_e32 v39, v76, v31
	v_fmac_f32_e32 v40, v78, v28
	v_fmac_f32_e32 v39, v77, v28
	s_waitcnt lgkmcnt(0)
	v_add_f32_dpp v3, v3, v3 row_half_mirror row_mask:0xf bank_mask:0xf
	s_nop 1
	v_fmac_f32_e32 v40, v79, v29
	v_fmac_f32_e32 v39, v78, v29
	v_fmac_f32_e32 v40, v80, v26
	v_fmac_f32_e32 v39, v79, v26
	s_waitcnt lgkmcnt(0)
	v_add_f32_dpp v3, v3, v3 row_mirror row_mask:0xf bank_mask:0xf
	v_mov_b32_e32 v6, v3
	s_nop 0
	v_fmac_f32_e32 v40, v81, v27
	v_fmac_f32_e32 v39, v80, v27
	v_fmac_f32_e32 v40, v82, v24
	v_fmac_f32_e32 v39, v81, v24
	s_waitcnt lgkmcnt(0)
	v_permlane16_swap_b32_e32 v3, v6
	v_add_f32_e32 v3, v3, v6
	v_mov_b32_e32 v6, v3
	s_nop 0
	v_fmac_f32_e32 v40, v83, v25
	v_fmac_f32_e32 v39, v82, v25
	v_fmac_f32_e32 v40, v84, v22
	v_fmac_f32_e32 v39, v83, v22
	s_waitcnt lgkmcnt(0)
	v_permlane32_swap_b32_e32 v3, v6
	v_add_f32_e32 v3, v3, v6
	v_fmac_f32_e32 v71, 0xbc800000, v3
	v_mul_f32_e32 v3, v71, v71
	s_nop 1
	v_fmac_f32_e32 v40, v85, v23
	v_fmac_f32_e32 v39, v84, v23
	v_fmac_f32_e32 v40, v86, v20
	v_fmac_f32_e32 v39, v85, v20
	s_waitcnt lgkmcnt(0)
	v_add_f32_dpp v3, v3, v3 quad_perm:[1,0,3,2] row_mask:0xf bank_mask:0xf
	s_nop 1
	v_fmac_f32_e32 v40, v87, v21
	v_fmac_f32_e32 v39, v86, v21
	v_fmac_f32_e32 v40, v88, v18
	v_fmac_f32_e32 v39, v87, v18
	s_waitcnt lgkmcnt(0)
	v_add_f32_dpp v3, v3, v3 quad_perm:[2,3,0,1] row_mask:0xf bank_mask:0xf
	s_nop 1
	v_fmac_f32_e32 v40, v89, v19
	v_fmac_f32_e32 v39, v88, v19
	v_fmac_f32_e32 v40, v90, v16
	v_fmac_f32_e32 v39, v89, v16
	s_waitcnt lgkmcnt(0)
	v_add_f32_dpp v3, v3, v3 row_half_mirror row_mask:0xf bank_mask:0xf
	s_nop 1
	v_fmac_f32_e32 v40, v91, v17
	v_fmac_f32_e32 v39, v90, v17
	v_fmac_f32_e32 v40, v92, v14
	v_fmac_f32_e32 v39, v91, v14
	s_waitcnt lgkmcnt(0)
; __device__ __forceinline__ bf16_t f2bf(float v) { return (bf16_t)(cvt_pk_bf16(v, 0.f) & 0xffffu); }
; __device__ __forceinline__ float sigmoidf_(float v) { return __builtin_amdgcn_rcpf(1.f + __expf(-v)); }
; __device__ __forceinline__ float wave_sum(float v) {
; #pragma unroll
;     for (int o = 1; o < 64; o <<= 1) v += __shfl_xor(v, o);
;     return v;
; }
; __device__ __forceinline__ void conv_item(const Params& p, LAS unsigned char* lds, int l, int item, const bf16_t* UC, bf16_t* MIXA) {
;     ...
; #pragma unroll
;     for (int i = 0; i < 32; ++i) {
;         const float mu = wave_sum(o[i]) * (1.f / 64.f);
;         const float d = o[i] - mu;
;         const float var = wave_sum(d * d) * (1.f / 64.f);
;         const float zn = d * __builtin_amdgcn_rsqf(var + EPSV) * lg + lb;
;         MIXA[(size_t)(rowbase + ts + i) * DM + 768 + ch] = f2bf(zn * sigmoidf_(zn));
;     }
	v_add_f32_dpp v3, v3, v3 row_mirror row_mask:0xf bank_mask:0xf
	v_mov_b32_e32 v6, v3
	s_nop 0
	v_fmac_f32_e32 v40, v93, v15
	v_fmac_f32_e32 v39, v92, v15
	v_fmac_f32_e32 v40, v94, v12
	v_fmac_f32_e32 v39, v93, v12
	s_waitcnt lgkmcnt(0)
	v_permlane16_swap_b32_e32 v3, v6
	v_add_f32_e32 v3, v3, v6
	v_mov_b32_e32 v6, v3
	s_nop 0
	v_fmac_f32_e32 v40, v95, v13
	v_fmac_f32_e32 v39, v94, v13
	v_fmac_f32_e32 v40, v96, v10
	v_fmac_f32_e32 v39, v95, v10
	s_waitcnt lgkmcnt(0)
	v_permlane32_swap_b32_e32 v3, v6
	v_add_f32_e32 v3, v3, v6
	v_fmamk_f32 v3, v3, 0x3c800000, v193
	v_rsq_f32_e32 v3, v3
	v_fmac_f32_e32 v40, v97, v11
	v_fmac_f32_e32 v39, v96, v11
	v_add_u32_e32 v2, s9, v66
	v_mul_f32_e32 v3, v71, v3
	s_waitcnt vmcnt(0)
	v_fma_f32 v3, v5, v3, v4
	v_mul_f32_e32 v6, 0xbfb8aa3b, v3
	v_exp_f32_e32 v6, v6
	v_fmac_f32_e32 v65, v98, v33
	v_fmac_f32_e32 v40, v98, v8
	v_fmac_f32_e32 v39, v97, v8
	v_add_f32_e32 v6, 1.0, v6
	v_rcp_f32_e32 v6, v6
	v_fmac_f32_e32 v37, v98, v7
	v_lshl_add_u64 v[0:1], s[0:1], 0, v[160:161]
	v_fmac_f32_e32 v64, v97, v33
	v_mul_f32_e32 v3, v3, v6
	v_cvt_pk_bf16_f32 v8, v3, v161
	v_ashrrev_i32_e32 v3, 31, v2
	v_lshlrev_b64 v[6:7], 11, v[2:3]
	s_nop 1
	v_lshl_add_u64 v[6:7], v[0:1], 0, v[6:7]
	global_store_short v[6:7], v8, off offset:1536
	v_fmac_f32_e32 v64, v98, v30
	v_fmac_f32_e32 v63, v96, v33
	s_waitcnt lgkmcnt(0)
	v_add_f32_dpp v3, v65, v65 quad_perm:[1,0,3,2] row_mask:0xf bank_mask:0xf
	s_nop 1
	v_fmac_f32_e32 v63, v97, v30
	v_fmac_f32_e32 v63, v98, v31
	v_fmac_f32_e32 v62, v95, v33
	v_fmac_f32_e32 v62, v96, v30
	s_waitcnt lgkmcnt(0)
	v_add_f32_dpp v3, v3, v3 quad_perm:[2,3,0,1] row_mask:0xf bank_mask:0xf
	s_nop 1
	v_fmac_f32_e32 v62, v97, v31
	v_fmac_f32_e32 v62, v98, v28
	v_fmac_f32_e32 v59, v94, v33
	v_fmac_f32_e32 v59, v95, v30
	s_waitcnt lgkmcnt(0)
	v_add_f32_dpp v3, v3, v3 row_half_mirror row_mask:0xf bank_mask:0xf
	s_nop 1
	v_fmac_f32_e32 v59, v96, v31
	v_fmac_f32_e32 v59, v97, v28
	v_fmac_f32_e32 v59, v98, v29
	v_fmac_f32_e32 v58, v93, v33
	s_waitcnt lgkmcnt(0)
	v_add_f32_dpp v3, v3, v3 row_mirror row_mask:0xf bank_mask:0xf
	v_mov_b32_e32 v6, v3
	s_nop 0
	v_fmac_f32_e32 v58, v94, v30
	v_fmac_f32_e32 v58, v95, v31
	v_fmac_f32_e32 v58, v96, v28
	v_fmac_f32_e32 v58, v97, v29
	s_waitcnt lgkmcnt(0)
	v_permlane16_swap_b32_e32 v3, v6
	v_add_f32_e32 v3, v3, v6
	v_mov_b32_e32 v6, v3
	s_nop 0
	v_fmac_f32_e32 v58, v98, v26
	v_fmac_f32_e32 v57, v92, v33
	v_fmac_f32_e32 v57, v93, v30
	v_fmac_f32_e32 v57, v94, v31
	s_waitcnt lgkmcnt(0)
	v_permlane32_swap_b32_e32 v3, v6
	v_add_f32_e32 v3, v3, v6
	v_fmac_f32_e32 v65, 0xbc800000, v3
	v_mul_f32_e32 v3, v65, v65
	s_nop 1
	v_fmac_f32_e32 v57, v95, v28
	v_fmac_f32_e32 v57, v96, v29
	v_fmac_f32_e32 v57, v97, v26
	v_fmac_f32_e32 v57, v98, v27
	s_waitcnt lgkmcnt(0)
	v_add_f32_dpp v3, v3, v3 quad_perm:[1,0,3,2] row_mask:0xf bank_mask:0xf
	s_nop 1
	v_fmac_f32_e32 v56, v91, v33
	v_fmac_f32_e32 v56, v92, v30
	v_fmac_f32_e32 v56, v93, v31
	v_fmac_f32_e32 v56, v94, v28
	s_waitcnt lgkmcnt(0)
	v_add_f32_dpp v3, v3, v3 quad_perm:[2,3,0,1] row_mask:0xf bank_mask:0xf
	s_nop 1
	v_fmac_f32_e32 v56, v95, v29
	v_fmac_f32_e32 v56, v96, v26
	v_fmac_f32_e32 v56, v97, v27
	v_fmac_f32_e32 v56, v98, v24
	s_waitcnt lgkmcnt(0)
	v_add_f32_dpp v3, v3, v3 row_half_mirror row_mask:0xf bank_mask:0xf
	s_nop 1
	v_fmac_f32_e32 v55, v90, v33
	v_fmac_f32_e32 v55, v91, v30
	v_fmac_f32_e32 v55, v92, v31
	v_fmac_f32_e32 v55, v93, v28
	s_waitcnt lgkmcnt(0)
	v_add_f32_dpp v3, v3, v3 row_mirror row_mask:0xf bank_mask:0xf
	v_mov_b32_e32 v6, v3
	s_nop 0
	v_fmac_f32_e32 v55, v94, v29
	v_fmac_f32_e32 v55, v95, v26
	v_fmac_f32_e32 v55, v96, v27
	v_fmac_f32_e32 v55, v97, v24
	s_waitcnt lgkmcnt(0)
	v_permlane16_swap_b32_e32 v3, v6
	v_add_f32_e32 v3, v3, v6
	v_mov_b32_e32 v6, v3
	s_nop 0
	v_fmac_f32_e32 v55, v98, v25
	v_fmac_f32_e32 v54, v89, v33
	v_fmac_f32_e32 v54, v90, v30
	v_fmac_f32_e32 v54, v91, v31
	s_waitcnt lgkmcnt(0)
	v_permlane32_swap_b32_e32 v3, v6
	v_add_f32_e32 v3, v3, v6
	v_fmamk_f32 v3, v3, 0x3c800000, v193
	v_rsq_f32_e32 v3, v3
	v_fmac_f32_e32 v54, v92, v28
	v_fmac_f32_e32 v54, v93, v29
	v_fmac_f32_e32 v54, v94, v26
	v_mul_f32_e32 v3, v65, v3
	v_fma_f32 v3, v5, v3, v4
	v_mul_f32_e32 v6, 0xbfb8aa3b, v3
	v_exp_f32_e32 v6, v6
	v_fmac_f32_e32 v54, v95, v27
	v_fmac_f32_e32 v54, v96, v24
	v_fmac_f32_e32 v54, v97, v25
	v_add_f32_e32 v6, 1.0, v6
	v_rcp_f32_e32 v6, v6
	v_fmac_f32_e32 v54, v98, v22
	v_fmac_f32_e32 v53, v88, v33
	v_fmac_f32_e32 v53, v89, v30
	v_mul_f32_e32 v3, v3, v6
	v_or_b32_e32 v6, 1, v2
	v_ashrrev_i32_e32 v7, 31, v6
	v_lshlrev_b64 v[6:7], 11, v[6:7]
	v_cvt_pk_bf16_f32 v3, v3, v161
	v_lshl_add_u64 v[6:7], v[0:1], 0, v[6:7]
	global_store_short v[6:7], v3, off offset:1536
	s_nop 1
	v_fmac_f32_e32 v53, v90, v31
	v_fmac_f32_e32 v53, v91, v28
	v_fmac_f32_e32 v53, v92, v29
	v_fmac_f32_e32 v53, v93, v26
	s_waitcnt lgkmcnt(0)
	v_add_f32_dpp v3, v64, v64 quad_perm:[1,0,3,2] row_mask:0xf bank_mask:0xf
	s_nop 1
	v_fmac_f32_e32 v53, v94, v27
	v_fmac_f32_e32 v53, v95, v24
	v_fmac_f32_e32 v53, v96, v25
	v_fmac_f32_e32 v53, v97, v22
	s_waitcnt lgkmcnt(0)
	v_add_f32_dpp v3, v3, v3 quad_perm:[2,3,0,1] row_mask:0xf bank_mask:0xf
	s_nop 1
	v_fmac_f32_e32 v53, v98, v23
	v_fmac_f32_e32 v52, v87, v33
	v_fmac_f32_e32 v52, v88, v30
	v_fmac_f32_e32 v52, v89, v31
	s_waitcnt lgkmcnt(0)
	v_add_f32_dpp v3, v3, v3 row_half_mirror row_mask:0xf bank_mask:0xf
	s_nop 1
	v_fmac_f32_e32 v52, v90, v28
	v_fmac_f32_e32 v52, v91, v29
	v_fmac_f32_e32 v52, v92, v26
	v_fmac_f32_e32 v52, v93, v27
	s_waitcnt lgkmcnt(0)
	v_add_f32_dpp v3, v3, v3 row_mirror row_mask:0xf bank_mask:0xf
	v_mov_b32_e32 v6, v3
	s_nop 0
	v_fmac_f32_e32 v52, v94, v24
	v_fmac_f32_e32 v52, v95, v25
	v_fmac_f32_e32 v52, v96, v22
	v_fmac_f32_e32 v52, v97, v23
	s_waitcnt lgkmcnt(0)
; __device__ __forceinline__ bf16_t f2bf(float v) { return (bf16_t)(cvt_pk_bf16(v, 0.f) & 0xffffu); }
; __device__ __forceinline__ float sigmoidf_(float v) { return __builtin_amdgcn_rcpf(1.f + __expf(-v)); }
; __device__ __forceinline__ float wave_sum(float v) {
; #pragma unroll
;     for (int o = 1; o < 64; o <<= 1) v += __shfl_xor(v, o);
;     return v;
; }
; __device__ __forceinline__ void conv_item(const Params& p, LAS unsigned char* lds, int l, int item, const bf16_t* UC, bf16_t* MIXA) {
;     ...
; #pragma unroll
;     for (int i = 0; i < 32; ++i) {
;         const float mu = wave_sum(o[i]) * (1.f / 64.f);
;         const float d = o[i] - mu;
;         const float var = wave_sum(d * d) * (1.f / 64.f);
;         const float zn = d * __builtin_amdgcn_rsqf(var + EPSV) * lg + lb;
;         MIXA[(size_t)(rowbase + ts + i) * DM + 768 + ch] = f2bf(zn * sigmoidf_(zn));
;     }
	v_permlane16_swap_b32_e32 v3, v6
	v_add_f32_e32 v3, v3, v6
	v_mov_b32_e32 v6, v3
	s_nop 0
	v_fmac_f32_e32 v52, v98, v20
	v_fmac_f32_e32 v51, v86, v33
	v_fmac_f32_e32 v51, v87, v30
	v_fmac_f32_e32 v51, v88, v31
	s_waitcnt lgkmcnt(0)
	v_permlane32_swap_b32_e32 v3, v6
	v_add_f32_e32 v3, v3, v6
	v_fmac_f32_e32 v64, 0xbc800000, v3
	v_mul_f32_e32 v3, v64, v64
	s_nop 1
	v_fmac_f32_e32 v51, v89, v28
	v_fmac_f32_e32 v51, v90, v29
	v_fmac_f32_e32 v51, v91, v26
	v_fmac_f32_e32 v51, v92, v27
	s_waitcnt lgkmcnt(0)
	v_add_f32_dpp v3, v3, v3 quad_perm:[1,0,3,2] row_mask:0xf bank_mask:0xf
	s_nop 1
	v_fmac_f32_e32 v51, v93, v24
	v_fmac_f32_e32 v51, v94, v25
	v_fmac_f32_e32 v51, v95, v22
	v_fmac_f32_e32 v51, v96, v23
	s_waitcnt lgkmcnt(0)
	v_add_f32_dpp v3, v3, v3 quad_perm:[2,3,0,1] row_mask:0xf bank_mask:0xf
	s_nop 1
	v_fmac_f32_e32 v51, v97, v20
	v_fmac_f32_e32 v51, v98, v21
	v_fmac_f32_e32 v50, v85, v33
	v_fmac_f32_e32 v50, v86, v30
	s_waitcnt lgkmcnt(0)
	v_add_f32_dpp v3, v3, v3 row_half_mirror row_mask:0xf bank_mask:0xf
	s_nop 1
	v_fmac_f32_e32 v50, v87, v31
	v_fmac_f32_e32 v50, v88, v28
	v_fmac_f32_e32 v50, v89, v29
	v_fmac_f32_e32 v50, v90, v26
	s_waitcnt lgkmcnt(0)
	v_add_f32_dpp v3, v3, v3 row_mirror row_mask:0xf bank_mask:0xf
	v_mov_b32_e32 v6, v3
	s_nop 0
	v_fmac_f32_e32 v50, v91, v27
	v_fmac_f32_e32 v50, v92, v24
	v_fmac_f32_e32 v50, v93, v25
	v_fmac_f32_e32 v50, v94, v22
	s_waitcnt lgkmcnt(0)
	v_permlane16_swap_b32_e32 v3, v6
	v_add_f32_e32 v3, v3, v6
	v_mov_b32_e32 v6, v3
	s_nop 0
	v_fmac_f32_e32 v50, v95, v23
	v_fmac_f32_e32 v50, v96, v20
	v_fmac_f32_e32 v50, v97, v21
	v_fmac_f32_e32 v50, v98, v18
	s_waitcnt lgkmcnt(0)
	v_permlane32_swap_b32_e32 v3, v6
	v_add_f32_e32 v3, v3, v6
	v_fmamk_f32 v3, v3, 0x3c800000, v193
	v_rsq_f32_e32 v3, v3
	v_fmac_f32_e32 v49, v84, v33
	v_fmac_f32_e32 v49, v85, v30
	v_fmac_f32_e32 v49, v86, v31
	v_mul_f32_e32 v3, v64, v3
	v_fma_f32 v3, v5, v3, v4
	v_mul_f32_e32 v6, 0xbfb8aa3b, v3
	v_exp_f32_e32 v6, v6
	v_fmac_f32_e32 v49, v87, v28
	v_fmac_f32_e32 v49, v88, v29
	v_fmac_f32_e32 v49, v89, v26
	v_add_f32_e32 v6, 1.0, v6
	v_rcp_f32_e32 v6, v6
	v_fmac_f32_e32 v49, v90, v27
	v_fmac_f32_e32 v49, v91, v24
	v_fmac_f32_e32 v49, v92, v25
	v_mul_f32_e32 v3, v3, v6
	v_or_b32_e32 v6, 2, v2
	v_ashrrev_i32_e32 v7, 31, v6
	v_lshlrev_b64 v[6:7], 11, v[6:7]
	v_cvt_pk_bf16_f32 v3, v3, v161
	v_lshl_add_u64 v[6:7], v[0:1], 0, v[6:7]
	global_store_short v[6:7], v3, off offset:1536
	s_nop 1
	v_fmac_f32_e32 v49, v93, v22
	v_fmac_f32_e32 v49, v94, v23
	v_fmac_f32_e32 v49, v95, v20
	v_fmac_f32_e32 v49, v96, v21
	s_waitcnt lgkmcnt(0)
	v_add_f32_dpp v3, v63, v63 quad_perm:[1,0,3,2] row_mask:0xf bank_mask:0xf
	s_nop 1
	v_fmac_f32_e32 v49, v97, v18
	v_fmac_f32_e32 v49, v98, v19
	v_fmac_f32_e32 v48, v83, v33
	v_fmac_f32_e32 v48, v84, v30
	s_waitcnt lgkmcnt(0)
	v_add_f32_dpp v3, v3, v3 quad_perm:[2,3,0,1] row_mask:0xf bank_mask:0xf
	s_nop 1
	v_fmac_f32_e32 v48, v85, v31
	v_fmac_f32_e32 v48, v86, v28
	v_fmac_f32_e32 v48, v87, v29
	v_fmac_f32_e32 v48, v88, v26
	s_waitcnt lgkmcnt(0)
	v_add_f32_dpp v3, v3, v3 row_half_mirror row_mask:0xf bank_mask:0xf
	s_nop 1
	v_fmac_f32_e32 v48, v89, v27
	v_fmac_f32_e32 v48, v90, v24
	v_fmac_f32_e32 v48, v91, v25
	v_fmac_f32_e32 v48, v92, v22
	s_waitcnt lgkmcnt(0)
	v_add_f32_dpp v3, v3, v3 row_mirror row_mask:0xf bank_mask:0xf
	v_mov_b32_e32 v6, v3
	s_nop 0
	v_fmac_f32_e32 v48, v93, v23
	v_fmac_f32_e32 v48, v94, v20
	v_fmac_f32_e32 v48, v95, v21
	v_fmac_f32_e32 v48, v96, v18
	s_waitcnt lgkmcnt(0)
	v_permlane16_swap_b32_e32 v3, v6
	v_add_f32_e32 v3, v3, v6
	v_mov_b32_e32 v6, v3
	s_nop 0
	v_fmac_f32_e32 v48, v97, v19
	v_fmac_f32_e32 v48, v98, v16
	v_fmac_f32_e32 v47, v82, v33
	v_fmac_f32_e32 v47, v83, v30
	s_waitcnt lgkmcnt(0)
	v_permlane32_swap_b32_e32 v3, v6
	v_add_f32_e32 v3, v3, v6
	v_fmac_f32_e32 v63, 0xbc800000, v3
	v_mul_f32_e32 v3, v63, v63
	s_nop 1
	v_fmac_f32_e32 v47, v84, v31
	v_fmac_f32_e32 v47, v85, v28
	v_fmac_f32_e32 v47, v86, v29
	v_fmac_f32_e32 v47, v87, v26
	s_waitcnt lgkmcnt(0)
	v_add_f32_dpp v3, v3, v3 quad_perm:[1,0,3,2] row_mask:0xf bank_mask:0xf
	s_nop 1
	v_fmac_f32_e32 v47, v88, v27
	v_fmac_f32_e32 v47, v89, v24
	v_fmac_f32_e32 v47, v90, v25
	v_fmac_f32_e32 v47, v91, v22
	s_waitcnt lgkmcnt(0)
	v_add_f32_dpp v3, v3, v3 quad_perm:[2,3,0,1] row_mask:0xf bank_mask:0xf
	s_nop 1
	v_fmac_f32_e32 v47, v92, v23
	v_fmac_f32_e32 v47, v93, v20
	v_fmac_f32_e32 v47, v94, v21
	v_fmac_f32_e32 v47, v95, v18
	s_waitcnt lgkmcnt(0)
	v_add_f32_dpp v3, v3, v3 row_half_mirror row_mask:0xf bank_mask:0xf
	s_nop 1
	v_fmac_f32_e32 v47, v96, v19
	v_fmac_f32_e32 v47, v97, v16
	v_fmac_f32_e32 v47, v98, v17
	v_fmac_f32_e32 v46, v81, v33
	s_waitcnt lgkmcnt(0)
	v_add_f32_dpp v3, v3, v3 row_mirror row_mask:0xf bank_mask:0xf
	v_mov_b32_e32 v6, v3
	s_nop 0
	v_fmac_f32_e32 v46, v82, v30
	v_fmac_f32_e32 v46, v83, v31
	v_fmac_f32_e32 v46, v84, v28
	v_fmac_f32_e32 v46, v85, v29
	s_waitcnt lgkmcnt(0)
	v_permlane16_swap_b32_e32 v3, v6
	v_add_f32_e32 v3, v3, v6
	v_mov_b32_e32 v6, v3
	s_nop 0
	v_fmac_f32_e32 v46, v86, v26
	v_fmac_f32_e32 v46, v87, v27
	v_fmac_f32_e32 v46, v88, v24
	v_fmac_f32_e32 v46, v89, v25
	s_waitcnt lgkmcnt(0)
	v_permlane32_swap_b32_e32 v3, v6
	v_add_f32_e32 v3, v3, v6
	v_fmamk_f32 v3, v3, 0x3c800000, v193
	v_rsq_f32_e32 v3, v3
	v_fmac_f32_e32 v46, v90, v22
	v_fmac_f32_e32 v46, v91, v23
	v_fmac_f32_e32 v46, v92, v20
	v_mul_f32_e32 v3, v63, v3
	v_fma_f32 v3, v5, v3, v4
	v_mul_f32_e32 v6, 0xbfb8aa3b, v3
	v_exp_f32_e32 v6, v6
	v_fmac_f32_e32 v46, v93, v21
	v_fmac_f32_e32 v46, v94, v18
	v_fmac_f32_e32 v46, v95, v19
	v_add_f32_e32 v6, 1.0, v6
	v_rcp_f32_e32 v6, v6
	v_fmac_f32_e32 v46, v96, v16
	v_fmac_f32_e32 v46, v97, v17
	v_fmac_f32_e32 v46, v98, v14
	v_mul_f32_e32 v3, v3, v6
	v_or_b32_e32 v6, 3, v2
	v_ashrrev_i32_e32 v7, 31, v6
	v_lshlrev_b64 v[6:7], 11, v[6:7]
	v_cvt_pk_bf16_f32 v3, v3, v161
	v_lshl_add_u64 v[6:7], v[0:1], 0, v[6:7]
	global_store_short v[6:7], v3, off offset:1536
	s_nop 1
	v_fmac_f32_e32 v45, v80, v33
	v_fmac_f32_e32 v45, v81, v30
	v_fmac_f32_e32 v45, v82, v31
	v_fmac_f32_e32 v45, v83, v28
	s_waitcnt lgkmcnt(0)
; __device__ __forceinline__ bf16_t f2bf(float v) { return (bf16_t)(cvt_pk_bf16(v, 0.f) & 0xffffu); }
; __device__ __forceinline__ float sigmoidf_(float v) { return __builtin_amdgcn_rcpf(1.f + __expf(-v)); }
; __device__ __forceinline__ float wave_sum(float v) {
; #pragma unroll
;     for (int o = 1; o < 64; o <<= 1) v += __shfl_xor(v, o);
;     return v;
; }
; __device__ __forceinline__ void conv_item(const Params& p, LAS unsigned char* lds, int l, int item, const bf16_t* UC, bf16_t* MIXA) {
;     ...
; #pragma unroll
;     for (int i = 0; i < 32; ++i) {
;         const float mu = wave_sum(o[i]) * (1.f / 64.f);
;         const float d = o[i] - mu;
;         const float var = wave_sum(d * d) * (1.f / 64.f);
;         const float zn = d * __builtin_amdgcn_rsqf(var + EPSV) * lg + lb;
;         MIXA[(size_t)(rowbase + ts + i) * DM + 768 + ch] = f2bf(zn * sigmoidf_(zn));
;     }
	v_add_f32_dpp v3, v62, v62 quad_perm:[1,0,3,2] row_mask:0xf bank_mask:0xf
	s_nop 1
	v_fmac_f32_e32 v45, v84, v29
	v_fmac_f32_e32 v45, v85, v26
	v_fmac_f32_e32 v45, v86, v27
	v_fmac_f32_e32 v45, v87, v24
	s_waitcnt lgkmcnt(0)
	v_add_f32_dpp v3, v3, v3 quad_perm:[2,3,0,1] row_mask:0xf bank_mask:0xf
	s_nop 1
	v_fmac_f32_e32 v45, v88, v25
	v_fmac_f32_e32 v45, v89, v22
	v_fmac_f32_e32 v45, v90, v23
	v_fmac_f32_e32 v45, v91, v20
	s_waitcnt lgkmcnt(0)
	v_add_f32_dpp v3, v3, v3 row_half_mirror row_mask:0xf bank_mask:0xf
	s_nop 1
	v_fmac_f32_e32 v45, v92, v21
	v_fmac_f32_e32 v45, v93, v18
	v_fmac_f32_e32 v45, v94, v19
	v_fmac_f32_e32 v45, v95, v16
	s_waitcnt lgkmcnt(0)
	v_add_f32_dpp v3, v3, v3 row_mirror row_mask:0xf bank_mask:0xf
	v_mov_b32_e32 v6, v3
	s_nop 0
	v_fmac_f32_e32 v45, v96, v17
	v_fmac_f32_e32 v45, v97, v14
	v_fmac_f32_e32 v45, v98, v15
	v_fmac_f32_e32 v44, v79, v33
	s_waitcnt lgkmcnt(0)
	v_permlane16_swap_b32_e32 v3, v6
	v_add_f32_e32 v3, v3, v6
	v_mov_b32_e32 v6, v3
	s_nop 0
	v_fmac_f32_e32 v44, v80, v30
	v_fmac_f32_e32 v44, v81, v31
	v_fmac_f32_e32 v44, v82, v28
	v_fmac_f32_e32 v44, v83, v29
	s_waitcnt lgkmcnt(0)
	v_permlane32_swap_b32_e32 v3, v6
	v_add_f32_e32 v3, v3, v6
	v_fmac_f32_e32 v62, 0xbc800000, v3
	v_mul_f32_e32 v3, v62, v62
	s_nop 1
	v_fmac_f32_e32 v44, v84, v26
	v_fmac_f32_e32 v44, v85, v27
	v_fmac_f32_e32 v44, v86, v24
	v_fmac_f32_e32 v44, v87, v25
	s_waitcnt lgkmcnt(0)
	v_add_f32_dpp v3, v3, v3 quad_perm:[1,0,3,2] row_mask:0xf bank_mask:0xf
	s_nop 1
	v_fmac_f32_e32 v44, v88, v22
	v_fmac_f32_e32 v44, v89, v23
	v_fmac_f32_e32 v44, v90, v20
	v_fmac_f32_e32 v44, v91, v21
	s_waitcnt lgkmcnt(0)
	v_add_f32_dpp v3, v3, v3 quad_perm:[2,3,0,1] row_mask:0xf bank_mask:0xf
	s_nop 1
	v_fmac_f32_e32 v44, v92, v18
	v_fmac_f32_e32 v44, v93, v19
	v_fmac_f32_e32 v44, v94, v16
	v_fmac_f32_e32 v44, v95, v17
	s_waitcnt lgkmcnt(0)
	v_add_f32_dpp v3, v3, v3 row_half_mirror row_mask:0xf bank_mask:0xf
	s_nop 1
	v_fmac_f32_e32 v44, v96, v14
	v_fmac_f32_e32 v44, v97, v15
	v_fmac_f32_e32 v44, v98, v12
	v_fmac_f32_e32 v43, v78, v33
	s_waitcnt lgkmcnt(0)
	v_add_f32_dpp v3, v3, v3 row_mirror row_mask:0xf bank_mask:0xf
	v_mov_b32_e32 v6, v3
	s_nop 0
	v_fmac_f32_e32 v43, v79, v30
	v_fmac_f32_e32 v43, v80, v31
	v_fmac_f32_e32 v43, v81, v28
	v_fmac_f32_e32 v43, v82, v29
	s_waitcnt lgkmcnt(0)
	v_permlane16_swap_b32_e32 v3, v6
	v_add_f32_e32 v3, v3, v6
	v_mov_b32_e32 v6, v3
	s_nop 0
	v_fmac_f32_e32 v43, v83, v26
	v_fmac_f32_e32 v43, v84, v27
	v_fmac_f32_e32 v43, v85, v24
	v_fmac_f32_e32 v43, v86, v25
	s_waitcnt lgkmcnt(0)
	v_permlane32_swap_b32_e32 v3, v6
	v_add_f32_e32 v3, v3, v6
	v_fmamk_f32 v3, v3, 0x3c800000, v193
	v_rsq_f32_e32 v3, v3
	v_fmac_f32_e32 v43, v87, v22
	v_fmac_f32_e32 v43, v88, v23
	v_fmac_f32_e32 v43, v89, v20
	v_mul_f32_e32 v3, v62, v3
	v_fma_f32 v3, v5, v3, v4
	v_mul_f32_e32 v6, 0xbfb8aa3b, v3
	v_exp_f32_e32 v6, v6
	v_fmac_f32_e32 v43, v90, v21
	v_fmac_f32_e32 v43, v91, v18
	v_fmac_f32_e32 v43, v92, v19
	v_add_f32_e32 v6, 1.0, v6
	v_rcp_f32_e32 v6, v6
	v_fmac_f32_e32 v43, v93, v16
	v_fmac_f32_e32 v43, v94, v17
	v_fmac_f32_e32 v43, v95, v14
	v_mul_f32_e32 v3, v3, v6
	v_or_b32_e32 v6, 4, v2
	v_ashrrev_i32_e32 v7, 31, v6
	v_lshlrev_b64 v[6:7], 11, v[6:7]
	v_cvt_pk_bf16_f32 v3, v3, v161
	v_lshl_add_u64 v[6:7], v[0:1], 0, v[6:7]
	global_store_short v[6:7], v3, off offset:1536
	s_nop 1
	v_fmac_f32_e32 v43, v96, v15
	v_fmac_f32_e32 v43, v97, v12
	v_fmac_f32_e32 v43, v98, v13
	v_fmac_f32_e32 v42, v77, v33
	s_waitcnt lgkmcnt(0)
	v_add_f32_dpp v3, v59, v59 quad_perm:[1,0,3,2] row_mask:0xf bank_mask:0xf
	s_nop 1
	v_fmac_f32_e32 v42, v78, v30
	v_fmac_f32_e32 v42, v79, v31
	v_fmac_f32_e32 v42, v80, v28
	v_fmac_f32_e32 v42, v81, v29
	s_waitcnt lgkmcnt(0)
	v_add_f32_dpp v3, v3, v3 quad_perm:[2,3,0,1] row_mask:0xf bank_mask:0xf
	s_nop 1
	v_fmac_f32_e32 v42, v82, v26
	v_fmac_f32_e32 v42, v83, v27
	v_fmac_f32_e32 v42, v84, v24
	v_fmac_f32_e32 v42, v85, v25
	s_waitcnt lgkmcnt(0)
	v_add_f32_dpp v3, v3, v3 row_half_mirror row_mask:0xf bank_mask:0xf
	s_nop 1
	v_fmac_f32_e32 v42, v86, v22
	v_fmac_f32_e32 v42, v87, v23
	v_fmac_f32_e32 v42, v88, v20
	v_fmac_f32_e32 v42, v89, v21
	s_waitcnt lgkmcnt(0)
	v_add_f32_dpp v3, v3, v3 row_mirror row_mask:0xf bank_mask:0xf
	v_mov_b32_e32 v6, v3
	s_nop 0
	v_fmac_f32_e32 v42, v90, v18
	v_fmac_f32_e32 v42, v91, v19
	v_fmac_f32_e32 v42, v92, v16
	v_fmac_f32_e32 v42, v93, v17
	s_waitcnt lgkmcnt(0)
	v_permlane16_swap_b32_e32 v3, v6
	v_add_f32_e32 v3, v3, v6
	v_mov_b32_e32 v6, v3
	s_nop 0
	v_fmac_f32_e32 v42, v94, v14
	v_fmac_f32_e32 v42, v95, v15
	v_fmac_f32_e32 v42, v96, v12
	v_fmac_f32_e32 v42, v97, v13
	s_waitcnt lgkmcnt(0)
	v_permlane32_swap_b32_e32 v3, v6
	v_add_f32_e32 v3, v3, v6
	v_fmac_f32_e32 v59, 0xbc800000, v3
	v_mul_f32_e32 v3, v59, v59
	s_nop 1
	v_fmac_f32_e32 v42, v98, v10
	v_fmac_f32_e32 v41, v76, v33
	v_fmac_f32_e32 v41, v77, v30
	v_fmac_f32_e32 v41, v78, v31
	s_waitcnt lgkmcnt(0)
	v_add_f32_dpp v3, v3, v3 quad_perm:[1,0,3,2] row_mask:0xf bank_mask:0xf
	s_nop 1
	v_fmac_f32_e32 v41, v79, v28
	v_fmac_f32_e32 v41, v80, v29
	v_fmac_f32_e32 v41, v81, v26
	v_fmac_f32_e32 v41, v82, v27
	s_waitcnt lgkmcnt(0)
	v_add_f32_dpp v3, v3, v3 quad_perm:[2,3,0,1] row_mask:0xf bank_mask:0xf
	s_nop 1
	v_fmac_f32_e32 v41, v83, v24
	v_fmac_f32_e32 v41, v84, v25
	v_fmac_f32_e32 v41, v85, v22
	v_fmac_f32_e32 v41, v86, v23
	s_waitcnt lgkmcnt(0)
	v_add_f32_dpp v3, v3, v3 row_half_mirror row_mask:0xf bank_mask:0xf
	s_nop 1
	v_fmac_f32_e32 v41, v87, v20
	v_fmac_f32_e32 v41, v88, v21
	v_fmac_f32_e32 v41, v89, v18
	v_fmac_f32_e32 v41, v90, v19
	s_waitcnt lgkmcnt(0)
; __device__ __forceinline__ bf16_t f2bf(float v) { return (bf16_t)(cvt_pk_bf16(v, 0.f) & 0xffffu); }
; __device__ __forceinline__ float sigmoidf_(float v) { return __builtin_amdgcn_rcpf(1.f + __expf(-v)); }
; __device__ __forceinline__ float wave_sum(float v) {
; #pragma unroll
;     for (int o = 1; o < 64; o <<= 1) v += __shfl_xor(v, o);
;     return v;
; }
; __device__ __forceinline__ void conv_item(const Params& p, LAS unsigned char* lds, int l, int item, const bf16_t* UC, bf16_t* MIXA) {
;     ...
; #pragma unroll
;     for (int i = 0; i < 32; ++i) {
;         const float mu = wave_sum(o[i]) * (1.f / 64.f);
;         const float d = o[i] - mu;
;         const float var = wave_sum(d * d) * (1.f / 64.f);
;         const float zn = d * __builtin_amdgcn_rsqf(var + EPSV) * lg + lb;
;         MIXA[(size_t)(rowbase + ts + i) * DM + 768 + ch] = f2bf(zn * sigmoidf_(zn));
;     }
	v_add_f32_dpp v3, v3, v3 row_mirror row_mask:0xf bank_mask:0xf
	v_mov_b32_e32 v6, v3
	s_nop 0
	v_fmac_f32_e32 v41, v91, v16
	v_fmac_f32_e32 v41, v92, v17
	v_fmac_f32_e32 v41, v93, v14
	v_fmac_f32_e32 v41, v94, v15
	s_waitcnt lgkmcnt(0)
	v_permlane16_swap_b32_e32 v3, v6
	v_add_f32_e32 v3, v3, v6
	v_mov_b32_e32 v6, v3
	s_nop 0
	v_fmac_f32_e32 v41, v95, v12
	v_fmac_f32_e32 v41, v96, v13
	v_fmac_f32_e32 v41, v97, v10
	v_fmac_f32_e32 v41, v98, v11
	s_waitcnt lgkmcnt(0)
	v_permlane32_swap_b32_e32 v3, v6
	v_add_f32_e32 v3, v3, v6
	v_fmamk_f32 v3, v3, 0x3c800000, v193
	v_rsq_f32_e32 v3, v3
	v_fmac_f32_e32 v39, v98, v9
	v_mul_f32_e32 v3, v59, v3
	v_fma_f32 v3, v5, v3, v4
	v_mul_f32_e32 v6, 0xbfb8aa3b, v3
	v_exp_f32_e32 v6, v6
	s_nop 0
	v_add_f32_e32 v6, 1.0, v6
	v_rcp_f32_e32 v6, v6
	s_nop 0
	v_mul_f32_e32 v3, v3, v6
	v_or_b32_e32 v6, 5, v2
	v_ashrrev_i32_e32 v7, 31, v6
	v_lshlrev_b64 v[6:7], 11, v[6:7]
	v_cvt_pk_bf16_f32 v3, v3, v161
	v_lshl_add_u64 v[6:7], v[0:1], 0, v[6:7]
	global_store_short v[6:7], v3, off offset:1536
	s_nop 1
	s_waitcnt lgkmcnt(0)
	v_add_f32_dpp v3, v58, v58 quad_perm:[1,0,3,2] row_mask:0xf bank_mask:0xf
	s_nop 1
	s_waitcnt lgkmcnt(0)
	v_add_f32_dpp v3, v3, v3 quad_perm:[2,3,0,1] row_mask:0xf bank_mask:0xf
	s_nop 1
	s_waitcnt lgkmcnt(0)
	v_add_f32_dpp v3, v3, v3 row_half_mirror row_mask:0xf bank_mask:0xf
	s_nop 1
	s_waitcnt lgkmcnt(0)
	v_add_f32_dpp v3, v3, v3 row_mirror row_mask:0xf bank_mask:0xf
	v_mov_b32_e32 v6, v3
	s_nop 0
	s_waitcnt lgkmcnt(0)
	v_permlane16_swap_b32_e32 v3, v6
	v_add_f32_e32 v3, v3, v6
	v_mov_b32_e32 v6, v3
	s_nop 0
	s_waitcnt lgkmcnt(0)
	v_permlane32_swap_b32_e32 v3, v6
	v_add_f32_e32 v3, v3, v6
	v_fmac_f32_e32 v58, 0xbc800000, v3
	v_mul_f32_e32 v3, v58, v58
	s_nop 1
	s_waitcnt lgkmcnt(0)
	v_add_f32_dpp v3, v3, v3 quad_perm:[1,0,3,2] row_mask:0xf bank_mask:0xf
	s_nop 1
	s_waitcnt lgkmcnt(0)
	v_add_f32_dpp v3, v3, v3 quad_perm:[2,3,0,1] row_mask:0xf bank_mask:0xf
	s_nop 1
	s_waitcnt lgkmcnt(0)
	v_add_f32_dpp v3, v3, v3 row_half_mirror row_mask:0xf bank_mask:0xf
	s_nop 1
	s_waitcnt lgkmcnt(0)
	v_add_f32_dpp v3, v3, v3 row_mirror row_mask:0xf bank_mask:0xf
	v_mov_b32_e32 v6, v3
	s_nop 0
	s_waitcnt lgkmcnt(0)
	v_permlane16_swap_b32_e32 v3, v6
	v_add_f32_e32 v3, v3, v6
	v_mov_b32_e32 v6, v3
	s_nop 0
	s_waitcnt lgkmcnt(0)
	v_permlane32_swap_b32_e32 v3, v6
	v_add_f32_e32 v3, v3, v6
	v_fmamk_f32 v3, v3, 0x3c800000, v193
	v_rsq_f32_e32 v3, v3
	s_nop 0
	v_mul_f32_e32 v3, v58, v3
	v_fma_f32 v3, v5, v3, v4
	v_mul_f32_e32 v6, 0xbfb8aa3b, v3
	v_exp_f32_e32 v6, v6
	s_nop 0
	v_add_f32_e32 v6, 1.0, v6
	v_rcp_f32_e32 v6, v6
	s_nop 0
	v_mul_f32_e32 v3, v3, v6
	v_or_b32_e32 v6, 6, v2
	v_ashrrev_i32_e32 v7, 31, v6
	v_lshlrev_b64 v[6:7], 11, v[6:7]
	v_cvt_pk_bf16_f32 v3, v3, v161
	v_lshl_add_u64 v[6:7], v[0:1], 0, v[6:7]
	global_store_short v[6:7], v3, off offset:1536
	s_nop 1
	s_waitcnt lgkmcnt(0)
	v_add_f32_dpp v3, v57, v57 quad_perm:[1,0,3,2] row_mask:0xf bank_mask:0xf
	s_nop 1
	s_waitcnt lgkmcnt(0)
	v_add_f32_dpp v3, v3, v3 quad_perm:[2,3,0,1] row_mask:0xf bank_mask:0xf
	s_nop 1
	s_waitcnt lgkmcnt(0)
	v_add_f32_dpp v3, v3, v3 row_half_mirror row_mask:0xf bank_mask:0xf
	s_nop 1
	s_waitcnt lgkmcnt(0)
	v_add_f32_dpp v3, v3, v3 row_mirror row_mask:0xf bank_mask:0xf
	v_mov_b32_e32 v6, v3
	s_nop 0
	s_waitcnt lgkmcnt(0)
	v_permlane16_swap_b32_e32 v3, v6
	v_add_f32_e32 v3, v3, v6
	v_mov_b32_e32 v6, v3
	s_nop 0
	s_waitcnt lgkmcnt(0)
	v_permlane32_swap_b32_e32 v3, v6
	v_add_f32_e32 v3, v3, v6
	v_fmac_f32_e32 v57, 0xbc800000, v3
	v_mul_f32_e32 v3, v57, v57
	s_nop 1
	s_waitcnt lgkmcnt(0)
	v_add_f32_dpp v3, v3, v3 quad_perm:[1,0,3,2] row_mask:0xf bank_mask:0xf
	s_nop 1
	s_waitcnt lgkmcnt(0)
	v_add_f32_dpp v3, v3, v3 quad_perm:[2,3,0,1] row_mask:0xf bank_mask:0xf
	s_nop 1
	s_waitcnt lgkmcnt(0)
	v_add_f32_dpp v3, v3, v3 row_half_mirror row_mask:0xf bank_mask:0xf
	s_nop 1
	s_waitcnt lgkmcnt(0)
	v_add_f32_dpp v3, v3, v3 row_mirror row_mask:0xf bank_mask:0xf
	v_mov_b32_e32 v6, v3
	s_nop 0
	s_waitcnt lgkmcnt(0)
	v_permlane16_swap_b32_e32 v3, v6
	v_add_f32_e32 v3, v3, v6
	v_mov_b32_e32 v6, v3
	s_nop 0
	s_waitcnt lgkmcnt(0)
	v_permlane32_swap_b32_e32 v3, v6
	v_add_f32_e32 v3, v3, v6
	v_fmamk_f32 v3, v3, 0x3c800000, v193
	v_rsq_f32_e32 v3, v3
	s_nop 0
	v_mul_f32_e32 v3, v57, v3
	v_fma_f32 v3, v5, v3, v4
	v_mul_f32_e32 v6, 0xbfb8aa3b, v3
	v_exp_f32_e32 v6, v6
	s_nop 0
	v_add_f32_e32 v6, 1.0, v6
	v_rcp_f32_e32 v6, v6
	s_nop 0
	v_mul_f32_e32 v3, v3, v6
	v_or_b32_e32 v6, 7, v2
	v_ashrrev_i32_e32 v7, 31, v6
	v_lshlrev_b64 v[6:7], 11, v[6:7]
	v_cvt_pk_bf16_f32 v3, v3, v161
	v_lshl_add_u64 v[6:7], v[0:1], 0, v[6:7]
	global_store_short v[6:7], v3, off offset:1536
	s_nop 1
	s_waitcnt lgkmcnt(0)
	v_add_f32_dpp v3, v56, v56 quad_perm:[1,0,3,2] row_mask:0xf bank_mask:0xf
	s_nop 1
	s_waitcnt lgkmcnt(0)
	v_add_f32_dpp v3, v3, v3 quad_perm:[2,3,0,1] row_mask:0xf bank_mask:0xf
	s_nop 1
	s_waitcnt lgkmcnt(0)
	v_add_f32_dpp v3, v3, v3 row_half_mirror row_mask:0xf bank_mask:0xf
	s_nop 1
	s_waitcnt lgkmcnt(0)
	v_add_f32_dpp v3, v3, v3 row_mirror row_mask:0xf bank_mask:0xf
	v_mov_b32_e32 v6, v3
	s_nop 0
	s_waitcnt lgkmcnt(0)
	v_permlane16_swap_b32_e32 v3, v6
	v_add_f32_e32 v3, v3, v6
	v_mov_b32_e32 v6, v3
	s_nop 0
	s_waitcnt lgkmcnt(0)
	v_permlane32_swap_b32_e32 v3, v6
	v_add_f32_e32 v3, v3, v6
	v_fmac_f32_e32 v56, 0xbc800000, v3
	v_mul_f32_e32 v3, v56, v56
	s_nop 1
	s_waitcnt lgkmcnt(0)
	v_add_f32_dpp v3, v3, v3 quad_perm:[1,0,3,2] row_mask:0xf bank_mask:0xf
	s_nop 1
	s_waitcnt lgkmcnt(0)
	v_add_f32_dpp v3, v3, v3 quad_perm:[2,3,0,1] row_mask:0xf bank_mask:0xf
	s_nop 1
	s_waitcnt lgkmcnt(0)
	v_add_f32_dpp v3, v3, v3 row_half_mirror row_mask:0xf bank_mask:0xf
	s_nop 1
	s_waitcnt lgkmcnt(0)
; __device__ __forceinline__ bf16_t f2bf(float v) { return (bf16_t)(cvt_pk_bf16(v, 0.f) & 0xffffu); }
; __device__ __forceinline__ float sigmoidf_(float v) { return __builtin_amdgcn_rcpf(1.f + __expf(-v)); }
; __device__ __forceinline__ float wave_sum(float v) {
; #pragma unroll
;     for (int o = 1; o < 64; o <<= 1) v += __shfl_xor(v, o);
;     return v;
; }
; __device__ __forceinline__ void conv_item(const Params& p, LAS unsigned char* lds, int l, int item, const bf16_t* UC, bf16_t* MIXA) {
;     ...
; #pragma unroll
;     for (int i = 0; i < 32; ++i) {
;         const float mu = wave_sum(o[i]) * (1.f / 64.f);
;         const float d = o[i] - mu;
;         const float var = wave_sum(d * d) * (1.f / 64.f);
;         const float zn = d * __builtin_amdgcn_rsqf(var + EPSV) * lg + lb;
;         MIXA[(size_t)(rowbase + ts + i) * DM + 768 + ch] = f2bf(zn * sigmoidf_(zn));
;     }
	v_add_f32_dpp v3, v3, v3 row_mirror row_mask:0xf bank_mask:0xf
	v_mov_b32_e32 v6, v3
	s_nop 0
	s_waitcnt lgkmcnt(0)
	v_permlane16_swap_b32_e32 v3, v6
	v_add_f32_e32 v3, v3, v6
	v_mov_b32_e32 v6, v3
	s_nop 0
	s_waitcnt lgkmcnt(0)
	v_permlane32_swap_b32_e32 v3, v6
	v_add_f32_e32 v3, v3, v6
	v_fmamk_f32 v3, v3, 0x3c800000, v193
	v_rsq_f32_e32 v3, v3
	s_nop 0
	v_mul_f32_e32 v3, v56, v3
	v_fma_f32 v3, v5, v3, v4
	v_mul_f32_e32 v6, 0xbfb8aa3b, v3
	v_exp_f32_e32 v6, v6
	s_nop 0
	v_add_f32_e32 v6, 1.0, v6
	v_rcp_f32_e32 v6, v6
	s_nop 0
	v_mul_f32_e32 v3, v3, v6
	v_or_b32_e32 v6, 8, v2
	v_ashrrev_i32_e32 v7, 31, v6
	v_lshlrev_b64 v[6:7], 11, v[6:7]
	v_cvt_pk_bf16_f32 v3, v3, v161
	v_lshl_add_u64 v[6:7], v[0:1], 0, v[6:7]
	global_store_short v[6:7], v3, off offset:1536
	s_nop 1
	s_waitcnt lgkmcnt(0)
	v_add_f32_dpp v3, v55, v55 quad_perm:[1,0,3,2] row_mask:0xf bank_mask:0xf
	s_nop 1
	s_waitcnt lgkmcnt(0)
	v_add_f32_dpp v3, v3, v3 quad_perm:[2,3,0,1] row_mask:0xf bank_mask:0xf
	s_nop 1
	s_waitcnt lgkmcnt(0)
	v_add_f32_dpp v3, v3, v3 row_half_mirror row_mask:0xf bank_mask:0xf
	s_nop 1
	s_waitcnt lgkmcnt(0)
	v_add_f32_dpp v3, v3, v3 row_mirror row_mask:0xf bank_mask:0xf
	v_mov_b32_e32 v6, v3
	s_nop 0
	s_waitcnt lgkmcnt(0)
	v_permlane16_swap_b32_e32 v3, v6
	v_add_f32_e32 v3, v3, v6
	v_mov_b32_e32 v6, v3
	s_nop 0
	s_waitcnt lgkmcnt(0)
	v_permlane32_swap_b32_e32 v3, v6
	v_add_f32_e32 v3, v3, v6
	v_fmac_f32_e32 v55, 0xbc800000, v3
	v_mul_f32_e32 v3, v55, v55
	s_nop 1
	s_waitcnt lgkmcnt(0)
	v_add_f32_dpp v3, v3, v3 quad_perm:[1,0,3,2] row_mask:0xf bank_mask:0xf
	s_nop 1
	s_waitcnt lgkmcnt(0)
	v_add_f32_dpp v3, v3, v3 quad_perm:[2,3,0,1] row_mask:0xf bank_mask:0xf
	s_nop 1
	s_waitcnt lgkmcnt(0)
	v_add_f32_dpp v3, v3, v3 row_half_mirror row_mask:0xf bank_mask:0xf
	s_nop 1
	s_waitcnt lgkmcnt(0)
	v_add_f32_dpp v3, v3, v3 row_mirror row_mask:0xf bank_mask:0xf
	v_mov_b32_e32 v6, v3
	s_nop 0
	s_waitcnt lgkmcnt(0)
	v_permlane16_swap_b32_e32 v3, v6
	v_add_f32_e32 v3, v3, v6
	v_mov_b32_e32 v6, v3
	s_nop 0
	s_waitcnt lgkmcnt(0)
	v_permlane32_swap_b32_e32 v3, v6
	v_add_f32_e32 v3, v3, v6
	v_fmamk_f32 v3, v3, 0x3c800000, v193
	v_rsq_f32_e32 v3, v3
	s_nop 0
	v_mul_f32_e32 v3, v55, v3
	v_fma_f32 v3, v5, v3, v4
	v_mul_f32_e32 v6, 0xbfb8aa3b, v3
	v_exp_f32_e32 v6, v6
	s_nop 0
	v_add_f32_e32 v6, 1.0, v6
	v_rcp_f32_e32 v6, v6
	s_nop 0
	v_mul_f32_e32 v3, v3, v6
	v_or_b32_e32 v6, 9, v2
	v_ashrrev_i32_e32 v7, 31, v6
	v_lshlrev_b64 v[6:7], 11, v[6:7]
	v_cvt_pk_bf16_f32 v3, v3, v161
	v_lshl_add_u64 v[6:7], v[0:1], 0, v[6:7]
	global_store_short v[6:7], v3, off offset:1536
	s_nop 1
	s_waitcnt lgkmcnt(0)
	v_add_f32_dpp v3, v54, v54 quad_perm:[1,0,3,2] row_mask:0xf bank_mask:0xf
	s_nop 1
	s_waitcnt lgkmcnt(0)
	v_add_f32_dpp v3, v3, v3 quad_perm:[2,3,0,1] row_mask:0xf bank_mask:0xf
	s_nop 1
	s_waitcnt lgkmcnt(0)
	v_add_f32_dpp v3, v3, v3 row_half_mirror row_mask:0xf bank_mask:0xf
	s_nop 1
	s_waitcnt lgkmcnt(0)
	v_add_f32_dpp v3, v3, v3 row_mirror row_mask:0xf bank_mask:0xf
	v_mov_b32_e32 v6, v3
	s_nop 0
	s_waitcnt lgkmcnt(0)
	v_permlane16_swap_b32_e32 v3, v6
	v_add_f32_e32 v3, v3, v6
	v_mov_b32_e32 v6, v3
	s_nop 0
	s_waitcnt lgkmcnt(0)
	v_permlane32_swap_b32_e32 v3, v6
	v_add_f32_e32 v3, v3, v6
	v_fmac_f32_e32 v54, 0xbc800000, v3
	v_mul_f32_e32 v3, v54, v54
	s_nop 1
	s_waitcnt lgkmcnt(0)
	v_add_f32_dpp v3, v3, v3 quad_perm:[1,0,3,2] row_mask:0xf bank_mask:0xf
	s_nop 1
	s_waitcnt lgkmcnt(0)
	v_add_f32_dpp v3, v3, v3 quad_perm:[2,3,0,1] row_mask:0xf bank_mask:0xf
	s_nop 1
	s_waitcnt lgkmcnt(0)
	v_add_f32_dpp v3, v3, v3 row_half_mirror row_mask:0xf bank_mask:0xf
	s_nop 1
	s_waitcnt lgkmcnt(0)
	v_add_f32_dpp v3, v3, v3 row_mirror row_mask:0xf bank_mask:0xf
	v_mov_b32_e32 v6, v3
	s_nop 0
	s_waitcnt lgkmcnt(0)
	v_permlane16_swap_b32_e32 v3, v6
	v_add_f32_e32 v3, v3, v6
	v_mov_b32_e32 v6, v3
	s_nop 0
	s_waitcnt lgkmcnt(0)
	v_permlane32_swap_b32_e32 v3, v6
	v_add_f32_e32 v3, v3, v6
	v_fmamk_f32 v3, v3, 0x3c800000, v193
	v_rsq_f32_e32 v3, v3
	s_nop 0
	v_mul_f32_e32 v3, v54, v3
	v_fma_f32 v3, v5, v3, v4
	v_mul_f32_e32 v6, 0xbfb8aa3b, v3
	v_exp_f32_e32 v6, v6
	s_nop 0
	v_add_f32_e32 v6, 1.0, v6
	v_rcp_f32_e32 v6, v6
	s_nop 0
	v_mul_f32_e32 v3, v3, v6
	v_or_b32_e32 v6, 10, v2
	v_ashrrev_i32_e32 v7, 31, v6
	v_lshlrev_b64 v[6:7], 11, v[6:7]
	v_cvt_pk_bf16_f32 v3, v3, v161
	v_lshl_add_u64 v[6:7], v[0:1], 0, v[6:7]
	global_store_short v[6:7], v3, off offset:1536
	s_nop 1
	s_waitcnt lgkmcnt(0)
	v_add_f32_dpp v3, v53, v53 quad_perm:[1,0,3,2] row_mask:0xf bank_mask:0xf
	s_nop 1
	s_waitcnt lgkmcnt(0)
	v_add_f32_dpp v3, v3, v3 quad_perm:[2,3,0,1] row_mask:0xf bank_mask:0xf
	s_nop 1
	s_waitcnt lgkmcnt(0)
	v_add_f32_dpp v3, v3, v3 row_half_mirror row_mask:0xf bank_mask:0xf
	s_nop 1
	s_waitcnt lgkmcnt(0)
	v_add_f32_dpp v3, v3, v3 row_mirror row_mask:0xf bank_mask:0xf
	v_mov_b32_e32 v6, v3
	s_nop 0
	s_waitcnt lgkmcnt(0)
	v_permlane16_swap_b32_e32 v3, v6
	v_add_f32_e32 v3, v3, v6
	v_mov_b32_e32 v6, v3
	s_nop 0
	s_waitcnt lgkmcnt(0)
	v_permlane32_swap_b32_e32 v3, v6
	v_add_f32_e32 v3, v3, v6
	v_fmac_f32_e32 v53, 0xbc800000, v3
	v_mul_f32_e32 v3, v53, v53
	s_nop 1
	s_waitcnt lgkmcnt(0)
	v_add_f32_dpp v3, v3, v3 quad_perm:[1,0,3,2] row_mask:0xf bank_mask:0xf
	s_nop 1
	s_waitcnt lgkmcnt(0)
	v_add_f32_dpp v3, v3, v3 quad_perm:[2,3,0,1] row_mask:0xf bank_mask:0xf
	s_nop 1
	s_waitcnt lgkmcnt(0)
	v_add_f32_dpp v3, v3, v3 row_half_mirror row_mask:0xf bank_mask:0xf
	s_nop 1
	s_waitcnt lgkmcnt(0)
	v_add_f32_dpp v3, v3, v3 row_mirror row_mask:0xf bank_mask:0xf
	v_mov_b32_e32 v6, v3
	s_nop 0
	s_waitcnt lgkmcnt(0)
	v_permlane16_swap_b32_e32 v3, v6
	v_add_f32_e32 v3, v3, v6
	v_mov_b32_e32 v6, v3
	s_nop 0
	s_waitcnt lgkmcnt(0)
; __device__ __forceinline__ bf16_t f2bf(float v) { return (bf16_t)(cvt_pk_bf16(v, 0.f) & 0xffffu); }
; __device__ __forceinline__ float sigmoidf_(float v) { return __builtin_amdgcn_rcpf(1.f + __expf(-v)); }
; __device__ __forceinline__ float wave_sum(float v) {
; #pragma unroll
;     for (int o = 1; o < 64; o <<= 1) v += __shfl_xor(v, o);
;     return v;
; }
; __device__ __forceinline__ void conv_item(const Params& p, LAS unsigned char* lds, int l, int item, const bf16_t* UC, bf16_t* MIXA) {
;     ...
; #pragma unroll
;     for (int i = 0; i < 32; ++i) {
;         const float mu = wave_sum(o[i]) * (1.f / 64.f);
;         const float d = o[i] - mu;
;         const float var = wave_sum(d * d) * (1.f / 64.f);
;         const float zn = d * __builtin_amdgcn_rsqf(var + EPSV) * lg + lb;
;         MIXA[(size_t)(rowbase + ts + i) * DM + 768 + ch] = f2bf(zn * sigmoidf_(zn));
;     }
	v_permlane32_swap_b32_e32 v3, v6
	v_add_f32_e32 v3, v3, v6
	v_fmamk_f32 v3, v3, 0x3c800000, v193
	v_rsq_f32_e32 v3, v3
	s_nop 0
	v_mul_f32_e32 v3, v53, v3
	v_fma_f32 v3, v5, v3, v4
	v_mul_f32_e32 v6, 0xbfb8aa3b, v3
	v_exp_f32_e32 v6, v6
	s_nop 0
	v_add_f32_e32 v6, 1.0, v6
	v_rcp_f32_e32 v6, v6
	s_nop 0
	v_mul_f32_e32 v3, v3, v6
	v_or_b32_e32 v6, 11, v2
	v_ashrrev_i32_e32 v7, 31, v6
	v_lshlrev_b64 v[6:7], 11, v[6:7]
	v_cvt_pk_bf16_f32 v3, v3, v161
	v_lshl_add_u64 v[6:7], v[0:1], 0, v[6:7]
	global_store_short v[6:7], v3, off offset:1536
	s_nop 1
	s_waitcnt lgkmcnt(0)
	v_add_f32_dpp v3, v52, v52 quad_perm:[1,0,3,2] row_mask:0xf bank_mask:0xf
	s_nop 1
	s_waitcnt lgkmcnt(0)
	v_add_f32_dpp v3, v3, v3 quad_perm:[2,3,0,1] row_mask:0xf bank_mask:0xf
	s_nop 1
	s_waitcnt lgkmcnt(0)
	v_add_f32_dpp v3, v3, v3 row_half_mirror row_mask:0xf bank_mask:0xf
	s_nop 1
	s_waitcnt lgkmcnt(0)
	v_add_f32_dpp v3, v3, v3 row_mirror row_mask:0xf bank_mask:0xf
	v_mov_b32_e32 v6, v3
	s_nop 0
	s_waitcnt lgkmcnt(0)
	v_permlane16_swap_b32_e32 v3, v6
	v_add_f32_e32 v3, v3, v6
	v_mov_b32_e32 v6, v3
	s_nop 0
	s_waitcnt lgkmcnt(0)
	v_permlane32_swap_b32_e32 v3, v6
	v_add_f32_e32 v3, v3, v6
	v_fmac_f32_e32 v52, 0xbc800000, v3
	v_mul_f32_e32 v3, v52, v52
	s_nop 1
	s_waitcnt lgkmcnt(0)
	v_add_f32_dpp v3, v3, v3 quad_perm:[1,0,3,2] row_mask:0xf bank_mask:0xf
	s_nop 1
	s_waitcnt lgkmcnt(0)
	v_add_f32_dpp v3, v3, v3 quad_perm:[2,3,0,1] row_mask:0xf bank_mask:0xf
	s_nop 1
	s_waitcnt lgkmcnt(0)
	v_add_f32_dpp v3, v3, v3 row_half_mirror row_mask:0xf bank_mask:0xf
	s_nop 1
	s_waitcnt lgkmcnt(0)
	v_add_f32_dpp v3, v3, v3 row_mirror row_mask:0xf bank_mask:0xf
	v_mov_b32_e32 v6, v3
	s_nop 0
	s_waitcnt lgkmcnt(0)
	v_permlane16_swap_b32_e32 v3, v6
	v_add_f32_e32 v3, v3, v6
	v_mov_b32_e32 v6, v3
	s_nop 0
	s_waitcnt lgkmcnt(0)
	v_permlane32_swap_b32_e32 v3, v6
	v_add_f32_e32 v3, v3, v6
	v_fmamk_f32 v3, v3, 0x3c800000, v193
	v_rsq_f32_e32 v3, v3
	s_nop 0
	v_mul_f32_e32 v3, v52, v3
	v_fma_f32 v3, v5, v3, v4
	v_mul_f32_e32 v6, 0xbfb8aa3b, v3
	v_exp_f32_e32 v6, v6
	s_nop 0
	v_add_f32_e32 v6, 1.0, v6
	v_rcp_f32_e32 v6, v6
	s_nop 0
	v_mul_f32_e32 v3, v3, v6
	v_or_b32_e32 v6, 12, v2
	v_ashrrev_i32_e32 v7, 31, v6
	v_lshlrev_b64 v[6:7], 11, v[6:7]
	v_cvt_pk_bf16_f32 v3, v3, v161
	v_lshl_add_u64 v[6:7], v[0:1], 0, v[6:7]
	global_store_short v[6:7], v3, off offset:1536
	s_nop 1
	s_waitcnt lgkmcnt(0)
	v_add_f32_dpp v3, v51, v51 quad_perm:[1,0,3,2] row_mask:0xf bank_mask:0xf
	s_nop 1
	s_waitcnt lgkmcnt(0)
	v_add_f32_dpp v3, v3, v3 quad_perm:[2,3,0,1] row_mask:0xf bank_mask:0xf
	s_nop 1
	s_waitcnt lgkmcnt(0)
	v_add_f32_dpp v3, v3, v3 row_half_mirror row_mask:0xf bank_mask:0xf
	s_nop 1
	s_waitcnt lgkmcnt(0)
	v_add_f32_dpp v3, v3, v3 row_mirror row_mask:0xf bank_mask:0xf
	v_mov_b32_e32 v6, v3
	s_nop 0
	s_waitcnt lgkmcnt(0)
	v_permlane16_swap_b32_e32 v3, v6
	v_add_f32_e32 v3, v3, v6
	v_mov_b32_e32 v6, v3
	s_nop 0
	s_waitcnt lgkmcnt(0)
	v_permlane32_swap_b32_e32 v3, v6
	v_add_f32_e32 v3, v3, v6
	v_fmac_f32_e32 v51, 0xbc800000, v3
	v_mul_f32_e32 v3, v51, v51
	s_nop 1
	s_waitcnt lgkmcnt(0)
	v_add_f32_dpp v3, v3, v3 quad_perm:[1,0,3,2] row_mask:0xf bank_mask:0xf
	s_nop 1
	s_waitcnt lgkmcnt(0)
	v_add_f32_dpp v3, v3, v3 quad_perm:[2,3,0,1] row_mask:0xf bank_mask:0xf
	s_nop 1
	s_waitcnt lgkmcnt(0)
	v_add_f32_dpp v3, v3, v3 row_half_mirror row_mask:0xf bank_mask:0xf
	s_nop 1
	s_waitcnt lgkmcnt(0)
	v_add_f32_dpp v3, v3, v3 row_mirror row_mask:0xf bank_mask:0xf
	v_mov_b32_e32 v6, v3
	s_nop 0
	s_waitcnt lgkmcnt(0)
	v_permlane16_swap_b32_e32 v3, v6
	v_add_f32_e32 v3, v3, v6
	v_mov_b32_e32 v6, v3
	s_nop 0
	s_waitcnt lgkmcnt(0)
	v_permlane32_swap_b32_e32 v3, v6
	v_add_f32_e32 v3, v3, v6
	v_fmamk_f32 v3, v3, 0x3c800000, v193
	v_rsq_f32_e32 v3, v3
	s_nop 0
	v_mul_f32_e32 v3, v51, v3
	v_fma_f32 v3, v5, v3, v4
	v_mul_f32_e32 v6, 0xbfb8aa3b, v3
	v_exp_f32_e32 v6, v6
	s_nop 0
	v_add_f32_e32 v6, 1.0, v6
	v_rcp_f32_e32 v6, v6
	s_nop 0
	v_mul_f32_e32 v3, v3, v6
	v_or_b32_e32 v6, 13, v2
	v_ashrrev_i32_e32 v7, 31, v6
	v_lshlrev_b64 v[6:7], 11, v[6:7]
	v_cvt_pk_bf16_f32 v3, v3, v161
	v_lshl_add_u64 v[6:7], v[0:1], 0, v[6:7]
	global_store_short v[6:7], v3, off offset:1536
	s_nop 1
	s_waitcnt lgkmcnt(0)
	v_add_f32_dpp v3, v50, v50 quad_perm:[1,0,3,2] row_mask:0xf bank_mask:0xf
	s_nop 1
	s_waitcnt lgkmcnt(0)
	v_add_f32_dpp v3, v3, v3 quad_perm:[2,3,0,1] row_mask:0xf bank_mask:0xf
	s_nop 1
	s_waitcnt lgkmcnt(0)
	v_add_f32_dpp v3, v3, v3 row_half_mirror row_mask:0xf bank_mask:0xf
	s_nop 1
	s_waitcnt lgkmcnt(0)
	v_add_f32_dpp v3, v3, v3 row_mirror row_mask:0xf bank_mask:0xf
	v_mov_b32_e32 v6, v3
	s_nop 0
	s_waitcnt lgkmcnt(0)
	v_permlane16_swap_b32_e32 v3, v6
	v_add_f32_e32 v3, v3, v6
	v_mov_b32_e32 v6, v3
	s_nop 0
	s_waitcnt lgkmcnt(0)
	v_permlane32_swap_b32_e32 v3, v6
	v_add_f32_e32 v3, v3, v6
	v_fmac_f32_e32 v50, 0xbc800000, v3
	v_mul_f32_e32 v3, v50, v50
	s_nop 1
	s_waitcnt lgkmcnt(0)
	v_add_f32_dpp v3, v3, v3 quad_perm:[1,0,3,2] row_mask:0xf bank_mask:0xf
	s_nop 1
	s_waitcnt lgkmcnt(0)
	v_add_f32_dpp v3, v3, v3 quad_perm:[2,3,0,1] row_mask:0xf bank_mask:0xf
	s_nop 1
	s_waitcnt lgkmcnt(0)
	v_add_f32_dpp v3, v3, v3 row_half_mirror row_mask:0xf bank_mask:0xf
	s_nop 1
	s_waitcnt lgkmcnt(0)
	v_add_f32_dpp v3, v3, v3 row_mirror row_mask:0xf bank_mask:0xf
	v_mov_b32_e32 v6, v3
	s_nop 0
	s_waitcnt lgkmcnt(0)
	v_permlane16_swap_b32_e32 v3, v6
	v_add_f32_e32 v3, v3, v6
	v_mov_b32_e32 v6, v3
	s_nop 0
	s_waitcnt lgkmcnt(0)
; __device__ __forceinline__ bf16_t f2bf(float v) { return (bf16_t)(cvt_pk_bf16(v, 0.f) & 0xffffu); }
; __device__ __forceinline__ float sigmoidf_(float v) { return __builtin_amdgcn_rcpf(1.f + __expf(-v)); }
; __device__ __forceinline__ float wave_sum(float v) {
; #pragma unroll
;     for (int o = 1; o < 64; o <<= 1) v += __shfl_xor(v, o);
;     return v;
; }
; __device__ __forceinline__ void conv_item(const Params& p, LAS unsigned char* lds, int l, int item, const bf16_t* UC, bf16_t* MIXA) {
;     ...
; #pragma unroll
;     for (int i = 0; i < 32; ++i) {
;         const float mu = wave_sum(o[i]) * (1.f / 64.f);
;         const float d = o[i] - mu;
;         const float var = wave_sum(d * d) * (1.f / 64.f);
;         const float zn = d * __builtin_amdgcn_rsqf(var + EPSV) * lg + lb;
;         MIXA[(size_t)(rowbase + ts + i) * DM + 768 + ch] = f2bf(zn * sigmoidf_(zn));
;     }
	v_permlane32_swap_b32_e32 v3, v6
	v_add_f32_e32 v3, v3, v6
	v_fmamk_f32 v3, v3, 0x3c800000, v193
	v_rsq_f32_e32 v3, v3
	s_nop 0
	v_mul_f32_e32 v3, v50, v3
	v_fma_f32 v3, v5, v3, v4
	v_mul_f32_e32 v6, 0xbfb8aa3b, v3
	v_exp_f32_e32 v6, v6
	s_nop 0
	v_add_f32_e32 v6, 1.0, v6
	v_rcp_f32_e32 v6, v6
	s_nop 0
	v_mul_f32_e32 v3, v3, v6
	v_or_b32_e32 v6, 14, v2
	v_ashrrev_i32_e32 v7, 31, v6
	v_lshlrev_b64 v[6:7], 11, v[6:7]
	v_cvt_pk_bf16_f32 v3, v3, v161
	v_lshl_add_u64 v[6:7], v[0:1], 0, v[6:7]
	global_store_short v[6:7], v3, off offset:1536
	s_nop 1
	s_waitcnt lgkmcnt(0)
	v_add_f32_dpp v3, v49, v49 quad_perm:[1,0,3,2] row_mask:0xf bank_mask:0xf
	s_nop 1
	s_waitcnt lgkmcnt(0)
	v_add_f32_dpp v3, v3, v3 quad_perm:[2,3,0,1] row_mask:0xf bank_mask:0xf
	s_nop 1
	s_waitcnt lgkmcnt(0)
	v_add_f32_dpp v3, v3, v3 row_half_mirror row_mask:0xf bank_mask:0xf
	s_nop 1
	s_waitcnt lgkmcnt(0)
	v_add_f32_dpp v3, v3, v3 row_mirror row_mask:0xf bank_mask:0xf
	v_mov_b32_e32 v6, v3
	s_nop 0
	s_waitcnt lgkmcnt(0)
	v_permlane16_swap_b32_e32 v3, v6
	v_add_f32_e32 v3, v3, v6
	v_mov_b32_e32 v6, v3
	s_nop 0
	s_waitcnt lgkmcnt(0)
	v_permlane32_swap_b32_e32 v3, v6
	v_add_f32_e32 v3, v3, v6
	v_fmac_f32_e32 v49, 0xbc800000, v3
	v_mul_f32_e32 v3, v49, v49
	s_nop 1
	s_waitcnt lgkmcnt(0)
	v_add_f32_dpp v3, v3, v3 quad_perm:[1,0,3,2] row_mask:0xf bank_mask:0xf
	s_nop 1
	s_waitcnt lgkmcnt(0)
	v_add_f32_dpp v3, v3, v3 quad_perm:[2,3,0,1] row_mask:0xf bank_mask:0xf
	s_nop 1
	s_waitcnt lgkmcnt(0)
	v_add_f32_dpp v3, v3, v3 row_half_mirror row_mask:0xf bank_mask:0xf
	s_nop 1
	s_waitcnt lgkmcnt(0)
	v_add_f32_dpp v3, v3, v3 row_mirror row_mask:0xf bank_mask:0xf
	v_mov_b32_e32 v6, v3
	s_nop 0
	s_waitcnt lgkmcnt(0)
	v_permlane16_swap_b32_e32 v3, v6
	v_add_f32_e32 v3, v3, v6
	v_mov_b32_e32 v6, v3
	s_nop 0
	s_waitcnt lgkmcnt(0)
	v_permlane32_swap_b32_e32 v3, v6
	v_add_f32_e32 v3, v3, v6
	v_fmamk_f32 v3, v3, 0x3c800000, v193
	v_rsq_f32_e32 v3, v3
	s_nop 0
	v_mul_f32_e32 v3, v49, v3
	v_fma_f32 v3, v5, v3, v4
	v_mul_f32_e32 v6, 0xbfb8aa3b, v3
	v_exp_f32_e32 v6, v6
	s_nop 0
	v_add_f32_e32 v6, 1.0, v6
	v_rcp_f32_e32 v6, v6
	s_nop 0
	v_mul_f32_e32 v3, v3, v6
	v_or_b32_e32 v6, 15, v2
	v_ashrrev_i32_e32 v7, 31, v6
	v_lshlrev_b64 v[6:7], 11, v[6:7]
	v_cvt_pk_bf16_f32 v3, v3, v161
	v_lshl_add_u64 v[6:7], v[0:1], 0, v[6:7]
	global_store_short v[6:7], v3, off offset:1536
	s_nop 1
	s_waitcnt lgkmcnt(0)
	v_add_f32_dpp v3, v48, v48 quad_perm:[1,0,3,2] row_mask:0xf bank_mask:0xf
	s_nop 1
	s_waitcnt lgkmcnt(0)
	v_add_f32_dpp v3, v3, v3 quad_perm:[2,3,0,1] row_mask:0xf bank_mask:0xf
	s_nop 1
	s_waitcnt lgkmcnt(0)
	v_add_f32_dpp v3, v3, v3 row_half_mirror row_mask:0xf bank_mask:0xf
	s_nop 1
	s_waitcnt lgkmcnt(0)
	v_add_f32_dpp v3, v3, v3 row_mirror row_mask:0xf bank_mask:0xf
	v_mov_b32_e32 v6, v3
	s_nop 0
	s_waitcnt lgkmcnt(0)
	v_permlane16_swap_b32_e32 v3, v6
	v_add_f32_e32 v3, v3, v6
	v_mov_b32_e32 v6, v3
	s_nop 0
	s_waitcnt lgkmcnt(0)
	v_permlane32_swap_b32_e32 v3, v6
	v_add_f32_e32 v3, v3, v6
	v_fmac_f32_e32 v48, 0xbc800000, v3
	v_mul_f32_e32 v3, v48, v48
	s_nop 1
	s_waitcnt lgkmcnt(0)
	v_add_f32_dpp v3, v3, v3 quad_perm:[1,0,3,2] row_mask:0xf bank_mask:0xf
	s_nop 1
	s_waitcnt lgkmcnt(0)
	v_add_f32_dpp v3, v3, v3 quad_perm:[2,3,0,1] row_mask:0xf bank_mask:0xf
	s_nop 1
	s_waitcnt lgkmcnt(0)
	v_add_f32_dpp v3, v3, v3 row_half_mirror row_mask:0xf bank_mask:0xf
	s_nop 1
	s_waitcnt lgkmcnt(0)
	v_add_f32_dpp v3, v3, v3 row_mirror row_mask:0xf bank_mask:0xf
	v_mov_b32_e32 v6, v3
	s_nop 0
	s_waitcnt lgkmcnt(0)
	v_permlane16_swap_b32_e32 v3, v6
	v_add_f32_e32 v3, v3, v6
	v_mov_b32_e32 v6, v3
	s_nop 0
	s_waitcnt lgkmcnt(0)
	v_permlane32_swap_b32_e32 v3, v6
	v_add_f32_e32 v3, v3, v6
	v_fmamk_f32 v3, v3, 0x3c800000, v193
	v_rsq_f32_e32 v3, v3
	s_nop 0
	v_mul_f32_e32 v3, v48, v3
	v_fma_f32 v3, v5, v3, v4
	v_mul_f32_e32 v6, 0xbfb8aa3b, v3
	v_exp_f32_e32 v6, v6
	s_nop 0
	v_add_f32_e32 v6, 1.0, v6
	v_rcp_f32_e32 v6, v6
	s_nop 0
	v_mul_f32_e32 v3, v3, v6
	v_or_b32_e32 v6, 16, v2
	v_ashrrev_i32_e32 v7, 31, v6
	v_lshlrev_b64 v[6:7], 11, v[6:7]
	v_cvt_pk_bf16_f32 v3, v3, v161
	v_lshl_add_u64 v[6:7], v[0:1], 0, v[6:7]
	global_store_short v[6:7], v3, off offset:1536
	s_nop 1
	s_waitcnt lgkmcnt(0)
	v_add_f32_dpp v3, v47, v47 quad_perm:[1,0,3,2] row_mask:0xf bank_mask:0xf
	s_nop 1
	s_waitcnt lgkmcnt(0)
	v_add_f32_dpp v3, v3, v3 quad_perm:[2,3,0,1] row_mask:0xf bank_mask:0xf
	s_nop 1
	s_waitcnt lgkmcnt(0)
	v_add_f32_dpp v3, v3, v3 row_half_mirror row_mask:0xf bank_mask:0xf
	s_nop 1
	s_waitcnt lgkmcnt(0)
	v_add_f32_dpp v3, v3, v3 row_mirror row_mask:0xf bank_mask:0xf
	v_mov_b32_e32 v6, v3
	s_nop 0
	s_waitcnt lgkmcnt(0)
	v_permlane16_swap_b32_e32 v3, v6
	v_add_f32_e32 v3, v3, v6
	v_mov_b32_e32 v6, v3
	s_nop 0
	s_waitcnt lgkmcnt(0)
	v_permlane32_swap_b32_e32 v3, v6
	v_add_f32_e32 v3, v3, v6
	v_fmac_f32_e32 v47, 0xbc800000, v3
	v_mul_f32_e32 v3, v47, v47
	s_nop 1
	s_waitcnt lgkmcnt(0)
	v_add_f32_dpp v3, v3, v3 quad_perm:[1,0,3,2] row_mask:0xf bank_mask:0xf
	s_nop 1
	s_waitcnt lgkmcnt(0)
	v_add_f32_dpp v3, v3, v3 quad_perm:[2,3,0,1] row_mask:0xf bank_mask:0xf
	s_nop 1
	s_waitcnt lgkmcnt(0)
	v_add_f32_dpp v3, v3, v3 row_half_mirror row_mask:0xf bank_mask:0xf
	s_nop 1
	s_waitcnt lgkmcnt(0)
	v_add_f32_dpp v3, v3, v3 row_mirror row_mask:0xf bank_mask:0xf
	v_mov_b32_e32 v6, v3
	s_nop 0
	s_waitcnt lgkmcnt(0)
	v_permlane16_swap_b32_e32 v3, v6
	v_add_f32_e32 v3, v3, v6
	v_mov_b32_e32 v6, v3
	s_nop 0
	s_waitcnt lgkmcnt(0)
; __device__ __forceinline__ bf16_t f2bf(float v) { return (bf16_t)(cvt_pk_bf16(v, 0.f) & 0xffffu); }
; __device__ __forceinline__ float sigmoidf_(float v) { return __builtin_amdgcn_rcpf(1.f + __expf(-v)); }
; __device__ __forceinline__ float wave_sum(float v) {
; #pragma unroll
;     for (int o = 1; o < 64; o <<= 1) v += __shfl_xor(v, o);
;     return v;
; }
; __device__ __forceinline__ void conv_item(const Params& p, LAS unsigned char* lds, int l, int item, const bf16_t* UC, bf16_t* MIXA) {
;     ...
; #pragma unroll
;     for (int i = 0; i < 32; ++i) {
;         const float mu = wave_sum(o[i]) * (1.f / 64.f);
;         const float d = o[i] - mu;
;         const float var = wave_sum(d * d) * (1.f / 64.f);
;         const float zn = d * __builtin_amdgcn_rsqf(var + EPSV) * lg + lb;
;         MIXA[(size_t)(rowbase + ts + i) * DM + 768 + ch] = f2bf(zn * sigmoidf_(zn));
;     }
	v_permlane32_swap_b32_e32 v3, v6
	v_add_f32_e32 v3, v3, v6
	v_fmamk_f32 v3, v3, 0x3c800000, v193
	v_rsq_f32_e32 v3, v3
	s_nop 0
	v_mul_f32_e32 v3, v47, v3
	v_fma_f32 v3, v5, v3, v4
	v_mul_f32_e32 v6, 0xbfb8aa3b, v3
	v_exp_f32_e32 v6, v6
	s_nop 0
	v_add_f32_e32 v6, 1.0, v6
	v_rcp_f32_e32 v6, v6
	s_nop 0
	v_mul_f32_e32 v3, v3, v6
	v_or_b32_e32 v6, 17, v2
	v_ashrrev_i32_e32 v7, 31, v6
	v_lshlrev_b64 v[6:7], 11, v[6:7]
	v_cvt_pk_bf16_f32 v3, v3, v161
	v_lshl_add_u64 v[6:7], v[0:1], 0, v[6:7]
	global_store_short v[6:7], v3, off offset:1536
	s_nop 1
	s_waitcnt lgkmcnt(0)
	v_add_f32_dpp v3, v46, v46 quad_perm:[1,0,3,2] row_mask:0xf bank_mask:0xf
	s_nop 1
	s_waitcnt lgkmcnt(0)
	v_add_f32_dpp v3, v3, v3 quad_perm:[2,3,0,1] row_mask:0xf bank_mask:0xf
	s_nop 1
	s_waitcnt lgkmcnt(0)
	v_add_f32_dpp v3, v3, v3 row_half_mirror row_mask:0xf bank_mask:0xf
	s_nop 1
	s_waitcnt lgkmcnt(0)
	v_add_f32_dpp v3, v3, v3 row_mirror row_mask:0xf bank_mask:0xf
	v_mov_b32_e32 v6, v3
	s_nop 0
	s_waitcnt lgkmcnt(0)
	v_permlane16_swap_b32_e32 v3, v6
	v_add_f32_e32 v3, v3, v6
	v_mov_b32_e32 v6, v3
	s_nop 0
	s_waitcnt lgkmcnt(0)
	v_permlane32_swap_b32_e32 v3, v6
	v_add_f32_e32 v3, v3, v6
	v_fmac_f32_e32 v46, 0xbc800000, v3
	v_mul_f32_e32 v3, v46, v46
	s_nop 1
	s_waitcnt lgkmcnt(0)
	v_add_f32_dpp v3, v3, v3 quad_perm:[1,0,3,2] row_mask:0xf bank_mask:0xf
	s_nop 1
	s_waitcnt lgkmcnt(0)
	v_add_f32_dpp v3, v3, v3 quad_perm:[2,3,0,1] row_mask:0xf bank_mask:0xf
	s_nop 1
	s_waitcnt lgkmcnt(0)
	v_add_f32_dpp v3, v3, v3 row_half_mirror row_mask:0xf bank_mask:0xf
	s_nop 1
	s_waitcnt lgkmcnt(0)
	v_add_f32_dpp v3, v3, v3 row_mirror row_mask:0xf bank_mask:0xf
	v_mov_b32_e32 v6, v3
	s_nop 0
	s_waitcnt lgkmcnt(0)
	v_permlane16_swap_b32_e32 v3, v6
	v_add_f32_e32 v3, v3, v6
	v_mov_b32_e32 v6, v3
	s_nop 0
	s_waitcnt lgkmcnt(0)
	v_permlane32_swap_b32_e32 v3, v6
	v_add_f32_e32 v3, v3, v6
	v_fmamk_f32 v3, v3, 0x3c800000, v193
	v_rsq_f32_e32 v3, v3
	s_nop 0
	v_mul_f32_e32 v3, v46, v3
	v_fma_f32 v3, v5, v3, v4
	v_mul_f32_e32 v6, 0xbfb8aa3b, v3
	v_exp_f32_e32 v6, v6
	s_nop 0
	v_add_f32_e32 v6, 1.0, v6
	v_rcp_f32_e32 v6, v6
	s_nop 0
	v_mul_f32_e32 v3, v3, v6
	v_or_b32_e32 v6, 18, v2
	v_ashrrev_i32_e32 v7, 31, v6
	v_lshlrev_b64 v[6:7], 11, v[6:7]
	v_cvt_pk_bf16_f32 v3, v3, v161
	v_lshl_add_u64 v[6:7], v[0:1], 0, v[6:7]
	global_store_short v[6:7], v3, off offset:1536
	s_nop 1
	s_waitcnt lgkmcnt(0)
	v_add_f32_dpp v3, v45, v45 quad_perm:[1,0,3,2] row_mask:0xf bank_mask:0xf
	s_nop 1
	s_waitcnt lgkmcnt(0)
	v_add_f32_dpp v3, v3, v3 quad_perm:[2,3,0,1] row_mask:0xf bank_mask:0xf
	s_nop 1
	s_waitcnt lgkmcnt(0)
	v_add_f32_dpp v3, v3, v3 row_half_mirror row_mask:0xf bank_mask:0xf
	s_nop 1
	s_waitcnt lgkmcnt(0)
	v_add_f32_dpp v3, v3, v3 row_mirror row_mask:0xf bank_mask:0xf
	v_mov_b32_e32 v6, v3
	s_nop 0
	s_waitcnt lgkmcnt(0)
	v_permlane16_swap_b32_e32 v3, v6
	v_add_f32_e32 v3, v3, v6
	v_mov_b32_e32 v6, v3
	s_nop 0
	s_waitcnt lgkmcnt(0)
	v_permlane32_swap_b32_e32 v3, v6
	v_add_f32_e32 v3, v3, v6
	v_fmac_f32_e32 v45, 0xbc800000, v3
	v_mul_f32_e32 v3, v45, v45
	s_nop 1
	s_waitcnt lgkmcnt(0)
	v_add_f32_dpp v3, v3, v3 quad_perm:[1,0,3,2] row_mask:0xf bank_mask:0xf
	s_nop 1
	s_waitcnt lgkmcnt(0)
	v_add_f32_dpp v3, v3, v3 quad_perm:[2,3,0,1] row_mask:0xf bank_mask:0xf
	s_nop 1
	s_waitcnt lgkmcnt(0)
	v_add_f32_dpp v3, v3, v3 row_half_mirror row_mask:0xf bank_mask:0xf
	s_nop 1
	s_waitcnt lgkmcnt(0)
	v_add_f32_dpp v3, v3, v3 row_mirror row_mask:0xf bank_mask:0xf
	v_mov_b32_e32 v6, v3
	s_nop 0
	s_waitcnt lgkmcnt(0)
	v_permlane16_swap_b32_e32 v3, v6
	v_add_f32_e32 v3, v3, v6
	v_mov_b32_e32 v6, v3
	s_nop 0
	s_waitcnt lgkmcnt(0)
	v_permlane32_swap_b32_e32 v3, v6
	v_add_f32_e32 v3, v3, v6
	v_fmamk_f32 v3, v3, 0x3c800000, v193
	v_rsq_f32_e32 v3, v3
	s_nop 0
	v_mul_f32_e32 v3, v45, v3
	v_fma_f32 v3, v5, v3, v4
	v_mul_f32_e32 v6, 0xbfb8aa3b, v3
	v_exp_f32_e32 v6, v6
	s_nop 0
	v_add_f32_e32 v6, 1.0, v6
	v_rcp_f32_e32 v6, v6
	s_nop 0
	v_mul_f32_e32 v3, v3, v6
	v_or_b32_e32 v6, 19, v2
	v_ashrrev_i32_e32 v7, 31, v6
	v_lshlrev_b64 v[6:7], 11, v[6:7]
	v_cvt_pk_bf16_f32 v3, v3, v161
	v_lshl_add_u64 v[6:7], v[0:1], 0, v[6:7]
	global_store_short v[6:7], v3, off offset:1536
	s_nop 1
	s_waitcnt lgkmcnt(0)
	v_add_f32_dpp v3, v44, v44 quad_perm:[1,0,3,2] row_mask:0xf bank_mask:0xf
	s_nop 1
	s_waitcnt lgkmcnt(0)
	v_add_f32_dpp v3, v3, v3 quad_perm:[2,3,0,1] row_mask:0xf bank_mask:0xf
	s_nop 1
	s_waitcnt lgkmcnt(0)
	v_add_f32_dpp v3, v3, v3 row_half_mirror row_mask:0xf bank_mask:0xf
	s_nop 1
	s_waitcnt lgkmcnt(0)
	v_add_f32_dpp v3, v3, v3 row_mirror row_mask:0xf bank_mask:0xf
	v_mov_b32_e32 v6, v3
	s_nop 0
	s_waitcnt lgkmcnt(0)
	v_permlane16_swap_b32_e32 v3, v6
	v_add_f32_e32 v3, v3, v6
	v_mov_b32_e32 v6, v3
	s_nop 0
	s_waitcnt lgkmcnt(0)
	v_permlane32_swap_b32_e32 v3, v6
	v_add_f32_e32 v3, v3, v6
	v_fmac_f32_e32 v44, 0xbc800000, v3
	v_mul_f32_e32 v3, v44, v44
	s_nop 1
	s_waitcnt lgkmcnt(0)
	v_add_f32_dpp v3, v3, v3 quad_perm:[1,0,3,2] row_mask:0xf bank_mask:0xf
	s_nop 1
	s_waitcnt lgkmcnt(0)
	v_add_f32_dpp v3, v3, v3 quad_perm:[2,3,0,1] row_mask:0xf bank_mask:0xf
	s_nop 1
	s_waitcnt lgkmcnt(0)
	v_add_f32_dpp v3, v3, v3 row_half_mirror row_mask:0xf bank_mask:0xf
	s_nop 1
	s_waitcnt lgkmcnt(0)
	v_add_f32_dpp v3, v3, v3 row_mirror row_mask:0xf bank_mask:0xf
	v_mov_b32_e32 v6, v3
	s_nop 0
	s_waitcnt lgkmcnt(0)
	v_permlane16_swap_b32_e32 v3, v6
	v_add_f32_e32 v3, v3, v6
	v_mov_b32_e32 v6, v3
	s_nop 0
	s_waitcnt lgkmcnt(0)
; __device__ __forceinline__ bf16_t f2bf(float v) { return (bf16_t)(cvt_pk_bf16(v, 0.f) & 0xffffu); }
; __device__ __forceinline__ float sigmoidf_(float v) { return __builtin_amdgcn_rcpf(1.f + __expf(-v)); }
; __device__ __forceinline__ float wave_sum(float v) {
; #pragma unroll
;     for (int o = 1; o < 64; o <<= 1) v += __shfl_xor(v, o);
;     return v;
; }
; __device__ __forceinline__ void conv_item(const Params& p, LAS unsigned char* lds, int l, int item, const bf16_t* UC, bf16_t* MIXA) {
;     ...
; #pragma unroll
;     for (int i = 0; i < 32; ++i) {
;         const float mu = wave_sum(o[i]) * (1.f / 64.f);
;         const float d = o[i] - mu;
;         const float var = wave_sum(d * d) * (1.f / 64.f);
;         const float zn = d * __builtin_amdgcn_rsqf(var + EPSV) * lg + lb;
;         MIXA[(size_t)(rowbase + ts + i) * DM + 768 + ch] = f2bf(zn * sigmoidf_(zn));
;     }
	v_permlane32_swap_b32_e32 v3, v6
	v_add_f32_e32 v3, v3, v6
	v_fmamk_f32 v3, v3, 0x3c800000, v193
	v_rsq_f32_e32 v3, v3
	s_nop 0
	v_mul_f32_e32 v3, v44, v3
	v_fma_f32 v3, v5, v3, v4
	v_mul_f32_e32 v6, 0xbfb8aa3b, v3
	v_exp_f32_e32 v6, v6
	s_nop 0
	v_add_f32_e32 v6, 1.0, v6
	v_rcp_f32_e32 v6, v6
	s_nop 0
	v_mul_f32_e32 v3, v3, v6
	v_or_b32_e32 v6, 20, v2
	v_ashrrev_i32_e32 v7, 31, v6
	v_lshlrev_b64 v[6:7], 11, v[6:7]
	v_cvt_pk_bf16_f32 v3, v3, v161
	v_lshl_add_u64 v[6:7], v[0:1], 0, v[6:7]
	global_store_short v[6:7], v3, off offset:1536
	s_nop 1
	s_waitcnt lgkmcnt(0)
	v_add_f32_dpp v3, v43, v43 quad_perm:[1,0,3,2] row_mask:0xf bank_mask:0xf
	s_nop 1
	s_waitcnt lgkmcnt(0)
	v_add_f32_dpp v3, v3, v3 quad_perm:[2,3,0,1] row_mask:0xf bank_mask:0xf
	s_nop 1
	s_waitcnt lgkmcnt(0)
	v_add_f32_dpp v3, v3, v3 row_half_mirror row_mask:0xf bank_mask:0xf
	s_nop 1
	s_waitcnt lgkmcnt(0)
	v_add_f32_dpp v3, v3, v3 row_mirror row_mask:0xf bank_mask:0xf
	v_mov_b32_e32 v6, v3
	s_nop 0
	s_waitcnt lgkmcnt(0)
	v_permlane16_swap_b32_e32 v3, v6
	v_add_f32_e32 v3, v3, v6
	v_mov_b32_e32 v6, v3
	s_nop 0
	s_waitcnt lgkmcnt(0)
	v_permlane32_swap_b32_e32 v3, v6
	v_add_f32_e32 v3, v3, v6
	v_fmac_f32_e32 v43, 0xbc800000, v3
	v_mul_f32_e32 v3, v43, v43
	s_nop 1
	s_waitcnt lgkmcnt(0)
	v_add_f32_dpp v3, v3, v3 quad_perm:[1,0,3,2] row_mask:0xf bank_mask:0xf
	s_nop 1
	s_waitcnt lgkmcnt(0)
	v_add_f32_dpp v3, v3, v3 quad_perm:[2,3,0,1] row_mask:0xf bank_mask:0xf
	s_nop 1
	s_waitcnt lgkmcnt(0)
	v_add_f32_dpp v3, v3, v3 row_half_mirror row_mask:0xf bank_mask:0xf
	s_nop 1
	s_waitcnt lgkmcnt(0)
	v_add_f32_dpp v3, v3, v3 row_mirror row_mask:0xf bank_mask:0xf
	v_mov_b32_e32 v6, v3
	s_nop 0
	s_waitcnt lgkmcnt(0)
	v_permlane16_swap_b32_e32 v3, v6
	v_add_f32_e32 v3, v3, v6
	v_mov_b32_e32 v6, v3
	s_nop 0
	s_waitcnt lgkmcnt(0)
	v_permlane32_swap_b32_e32 v3, v6
	v_add_f32_e32 v3, v3, v6
	v_fmamk_f32 v3, v3, 0x3c800000, v193
	v_rsq_f32_e32 v3, v3
	s_nop 0
	v_mul_f32_e32 v3, v43, v3
	v_fma_f32 v3, v5, v3, v4
	v_mul_f32_e32 v6, 0xbfb8aa3b, v3
	v_exp_f32_e32 v6, v6
	s_nop 0
	v_add_f32_e32 v6, 1.0, v6
	v_rcp_f32_e32 v6, v6
	s_nop 0
	v_mul_f32_e32 v3, v3, v6
	v_or_b32_e32 v6, 21, v2
	v_ashrrev_i32_e32 v7, 31, v6
	v_lshlrev_b64 v[6:7], 11, v[6:7]
	v_cvt_pk_bf16_f32 v3, v3, v161
	v_lshl_add_u64 v[6:7], v[0:1], 0, v[6:7]
	global_store_short v[6:7], v3, off offset:1536
	s_nop 1
	s_waitcnt lgkmcnt(0)
	v_add_f32_dpp v3, v42, v42 quad_perm:[1,0,3,2] row_mask:0xf bank_mask:0xf
	s_nop 1
	s_waitcnt lgkmcnt(0)
	v_add_f32_dpp v3, v3, v3 quad_perm:[2,3,0,1] row_mask:0xf bank_mask:0xf
	s_nop 1
	s_waitcnt lgkmcnt(0)
	v_add_f32_dpp v3, v3, v3 row_half_mirror row_mask:0xf bank_mask:0xf
	s_nop 1
	s_waitcnt lgkmcnt(0)
	v_add_f32_dpp v3, v3, v3 row_mirror row_mask:0xf bank_mask:0xf
	v_mov_b32_e32 v6, v3
	s_nop 0
	s_waitcnt lgkmcnt(0)
	v_permlane16_swap_b32_e32 v3, v6
	v_add_f32_e32 v3, v3, v6
	v_mov_b32_e32 v6, v3
	s_nop 0
	s_waitcnt lgkmcnt(0)
	v_permlane32_swap_b32_e32 v3, v6
	v_add_f32_e32 v3, v3, v6
	v_fmac_f32_e32 v42, 0xbc800000, v3
	v_mul_f32_e32 v3, v42, v42
	s_nop 1
	s_waitcnt lgkmcnt(0)
	v_add_f32_dpp v3, v3, v3 quad_perm:[1,0,3,2] row_mask:0xf bank_mask:0xf
	s_nop 1
	s_waitcnt lgkmcnt(0)
	v_add_f32_dpp v3, v3, v3 quad_perm:[2,3,0,1] row_mask:0xf bank_mask:0xf
	s_nop 1
	s_waitcnt lgkmcnt(0)
	v_add_f32_dpp v3, v3, v3 row_half_mirror row_mask:0xf bank_mask:0xf
	s_nop 1
	s_waitcnt lgkmcnt(0)
	v_add_f32_dpp v3, v3, v3 row_mirror row_mask:0xf bank_mask:0xf
	v_mov_b32_e32 v6, v3
	s_nop 0
	s_waitcnt lgkmcnt(0)
	v_permlane16_swap_b32_e32 v3, v6
	v_add_f32_e32 v3, v3, v6
	v_mov_b32_e32 v6, v3
	s_nop 0
	s_waitcnt lgkmcnt(0)
	v_permlane32_swap_b32_e32 v3, v6
	v_add_f32_e32 v3, v3, v6
	v_fmamk_f32 v3, v3, 0x3c800000, v193
	v_rsq_f32_e32 v3, v3
	s_nop 0
	v_mul_f32_e32 v3, v42, v3
	v_fma_f32 v3, v5, v3, v4
	v_mul_f32_e32 v6, 0xbfb8aa3b, v3
	v_exp_f32_e32 v6, v6
	s_nop 0
	v_add_f32_e32 v6, 1.0, v6
	v_rcp_f32_e32 v6, v6
	s_nop 0
	v_mul_f32_e32 v3, v3, v6
	v_or_b32_e32 v6, 22, v2
	v_ashrrev_i32_e32 v7, 31, v6
	v_lshlrev_b64 v[6:7], 11, v[6:7]
	v_cvt_pk_bf16_f32 v3, v3, v161
	v_lshl_add_u64 v[6:7], v[0:1], 0, v[6:7]
	global_store_short v[6:7], v3, off offset:1536
	s_nop 1
	s_waitcnt lgkmcnt(0)
	v_add_f32_dpp v3, v41, v41 quad_perm:[1,0,3,2] row_mask:0xf bank_mask:0xf
	s_nop 1
	s_waitcnt lgkmcnt(0)
	v_add_f32_dpp v3, v3, v3 quad_perm:[2,3,0,1] row_mask:0xf bank_mask:0xf
	s_nop 1
	s_waitcnt lgkmcnt(0)
	v_add_f32_dpp v3, v3, v3 row_half_mirror row_mask:0xf bank_mask:0xf
	s_nop 1
	s_waitcnt lgkmcnt(0)
	v_add_f32_dpp v3, v3, v3 row_mirror row_mask:0xf bank_mask:0xf
	v_mov_b32_e32 v6, v3
	s_nop 0
	s_waitcnt lgkmcnt(0)
	v_permlane16_swap_b32_e32 v3, v6
	v_add_f32_e32 v3, v3, v6
	v_mov_b32_e32 v6, v3
	s_nop 0
	s_waitcnt lgkmcnt(0)
	v_permlane32_swap_b32_e32 v3, v6
	v_add_f32_e32 v3, v3, v6
	v_fmac_f32_e32 v41, 0xbc800000, v3
	v_mul_f32_e32 v3, v41, v41
	s_nop 1
	s_waitcnt lgkmcnt(0)
	v_add_f32_dpp v3, v3, v3 quad_perm:[1,0,3,2] row_mask:0xf bank_mask:0xf
	s_nop 1
	s_waitcnt lgkmcnt(0)
	v_add_f32_dpp v3, v3, v3 quad_perm:[2,3,0,1] row_mask:0xf bank_mask:0xf
	s_nop 1
	s_waitcnt lgkmcnt(0)
	v_add_f32_dpp v3, v3, v3 row_half_mirror row_mask:0xf bank_mask:0xf
	s_nop 1
	s_waitcnt lgkmcnt(0)
	v_add_f32_dpp v3, v3, v3 row_mirror row_mask:0xf bank_mask:0xf
	v_mov_b32_e32 v6, v3
	s_nop 0
	s_waitcnt lgkmcnt(0)
	v_permlane16_swap_b32_e32 v3, v6
	v_add_f32_e32 v3, v3, v6
	v_mov_b32_e32 v6, v3
	s_nop 0
	s_waitcnt lgkmcnt(0)
; __device__ __forceinline__ bf16_t f2bf(float v) { return (bf16_t)(cvt_pk_bf16(v, 0.f) & 0xffffu); }
; __device__ __forceinline__ float sigmoidf_(float v) { return __builtin_amdgcn_rcpf(1.f + __expf(-v)); }
; __device__ __forceinline__ float wave_sum(float v) {
; #pragma unroll
;     for (int o = 1; o < 64; o <<= 1) v += __shfl_xor(v, o);
;     return v;
; }
; __device__ __forceinline__ void conv_item(const Params& p, LAS unsigned char* lds, int l, int item, const bf16_t* UC, bf16_t* MIXA) {
;     ...
; #pragma unroll
;     for (int i = 0; i < 32; ++i) {
;         const float mu = wave_sum(o[i]) * (1.f / 64.f);
;         const float d = o[i] - mu;
;         const float var = wave_sum(d * d) * (1.f / 64.f);
;         const float zn = d * __builtin_amdgcn_rsqf(var + EPSV) * lg + lb;
;         MIXA[(size_t)(rowbase + ts + i) * DM + 768 + ch] = f2bf(zn * sigmoidf_(zn));
;     }
	v_permlane32_swap_b32_e32 v3, v6
	v_add_f32_e32 v3, v3, v6
	v_fmamk_f32 v3, v3, 0x3c800000, v193
	v_rsq_f32_e32 v3, v3
	s_nop 0
	v_mul_f32_e32 v3, v41, v3
	v_fma_f32 v3, v5, v3, v4
	v_mul_f32_e32 v6, 0xbfb8aa3b, v3
	v_exp_f32_e32 v6, v6
	s_nop 0
	v_add_f32_e32 v6, 1.0, v6
	v_rcp_f32_e32 v6, v6
	s_nop 0
	v_mul_f32_e32 v3, v3, v6
	v_or_b32_e32 v6, 23, v2
	v_ashrrev_i32_e32 v7, 31, v6
	v_lshlrev_b64 v[6:7], 11, v[6:7]
	v_cvt_pk_bf16_f32 v3, v3, v161
	v_lshl_add_u64 v[6:7], v[0:1], 0, v[6:7]
	global_store_short v[6:7], v3, off offset:1536
	s_nop 1
	s_waitcnt lgkmcnt(0)
	v_add_f32_dpp v3, v40, v40 quad_perm:[1,0,3,2] row_mask:0xf bank_mask:0xf
	s_nop 1
	s_waitcnt lgkmcnt(0)
	v_add_f32_dpp v3, v3, v3 quad_perm:[2,3,0,1] row_mask:0xf bank_mask:0xf
	s_nop 1
	s_waitcnt lgkmcnt(0)
	v_add_f32_dpp v3, v3, v3 row_half_mirror row_mask:0xf bank_mask:0xf
	s_nop 1
	s_waitcnt lgkmcnt(0)
	v_add_f32_dpp v3, v3, v3 row_mirror row_mask:0xf bank_mask:0xf
	v_mov_b32_e32 v6, v3
	s_nop 0
	s_waitcnt lgkmcnt(0)
	v_permlane16_swap_b32_e32 v3, v6
	v_add_f32_e32 v3, v3, v6
	v_mov_b32_e32 v6, v3
	s_nop 0
	s_waitcnt lgkmcnt(0)
	v_permlane32_swap_b32_e32 v3, v6
	v_add_f32_e32 v3, v3, v6
	v_fmac_f32_e32 v40, 0xbc800000, v3
	v_mul_f32_e32 v3, v40, v40
	s_nop 1
	s_waitcnt lgkmcnt(0)
	v_add_f32_dpp v3, v3, v3 quad_perm:[1,0,3,2] row_mask:0xf bank_mask:0xf
	s_nop 1
	s_waitcnt lgkmcnt(0)
	v_add_f32_dpp v3, v3, v3 quad_perm:[2,3,0,1] row_mask:0xf bank_mask:0xf
	s_nop 1
	s_waitcnt lgkmcnt(0)
	v_add_f32_dpp v3, v3, v3 row_half_mirror row_mask:0xf bank_mask:0xf
	s_nop 1
	s_waitcnt lgkmcnt(0)
	v_add_f32_dpp v3, v3, v3 row_mirror row_mask:0xf bank_mask:0xf
	v_mov_b32_e32 v6, v3
	s_nop 0
	s_waitcnt lgkmcnt(0)
	v_permlane16_swap_b32_e32 v3, v6
	v_add_f32_e32 v3, v3, v6
	v_mov_b32_e32 v6, v3
	s_nop 0
	s_waitcnt lgkmcnt(0)
	v_permlane32_swap_b32_e32 v3, v6
	v_add_f32_e32 v3, v3, v6
	v_fmamk_f32 v3, v3, 0x3c800000, v193
	v_rsq_f32_e32 v3, v3
	s_nop 0
	v_mul_f32_e32 v3, v40, v3
	v_fma_f32 v3, v5, v3, v4
	v_mul_f32_e32 v6, 0xbfb8aa3b, v3
	v_exp_f32_e32 v6, v6
	s_nop 0
	v_add_f32_e32 v6, 1.0, v6
	v_rcp_f32_e32 v6, v6
	s_nop 0
	v_mul_f32_e32 v3, v3, v6
	v_or_b32_e32 v6, 24, v2
	v_ashrrev_i32_e32 v7, 31, v6
	v_lshlrev_b64 v[6:7], 11, v[6:7]
	v_cvt_pk_bf16_f32 v3, v3, v161
	v_lshl_add_u64 v[6:7], v[0:1], 0, v[6:7]
	global_store_short v[6:7], v3, off offset:1536
	s_nop 1
	s_waitcnt lgkmcnt(0)
	v_add_f32_dpp v3, v39, v39 quad_perm:[1,0,3,2] row_mask:0xf bank_mask:0xf
	s_nop 1
	s_waitcnt lgkmcnt(0)
	v_add_f32_dpp v3, v3, v3 quad_perm:[2,3,0,1] row_mask:0xf bank_mask:0xf
	s_nop 1
	s_waitcnt lgkmcnt(0)
	v_add_f32_dpp v3, v3, v3 row_half_mirror row_mask:0xf bank_mask:0xf
	s_nop 1
	s_waitcnt lgkmcnt(0)
	v_add_f32_dpp v3, v3, v3 row_mirror row_mask:0xf bank_mask:0xf
	v_mov_b32_e32 v6, v3
	s_nop 0
	s_waitcnt lgkmcnt(0)
	v_permlane16_swap_b32_e32 v3, v6
	v_add_f32_e32 v3, v3, v6
	v_mov_b32_e32 v6, v3
	s_nop 0
	s_waitcnt lgkmcnt(0)
	v_permlane32_swap_b32_e32 v3, v6
	v_add_f32_e32 v3, v3, v6
	v_fmac_f32_e32 v39, 0xbc800000, v3
	v_mul_f32_e32 v3, v39, v39
	s_nop 1
	s_waitcnt lgkmcnt(0)
	v_add_f32_dpp v3, v3, v3 quad_perm:[1,0,3,2] row_mask:0xf bank_mask:0xf
	s_nop 1
	s_waitcnt lgkmcnt(0)
	v_add_f32_dpp v3, v3, v3 quad_perm:[2,3,0,1] row_mask:0xf bank_mask:0xf
	s_nop 1
	s_waitcnt lgkmcnt(0)
	v_add_f32_dpp v3, v3, v3 row_half_mirror row_mask:0xf bank_mask:0xf
	s_nop 1
	s_waitcnt lgkmcnt(0)
	v_add_f32_dpp v3, v3, v3 row_mirror row_mask:0xf bank_mask:0xf
	v_mov_b32_e32 v6, v3
	s_nop 0
	s_waitcnt lgkmcnt(0)
	v_permlane16_swap_b32_e32 v3, v6
	v_add_f32_e32 v3, v3, v6
	v_mov_b32_e32 v6, v3
	s_nop 0
	s_waitcnt lgkmcnt(0)
	v_permlane32_swap_b32_e32 v3, v6
	v_add_f32_e32 v3, v3, v6
	v_fmamk_f32 v3, v3, 0x3c800000, v193
	v_rsq_f32_e32 v3, v3
	s_nop 0
	v_mul_f32_e32 v3, v39, v3
	v_fma_f32 v3, v5, v3, v4
	v_mul_f32_e32 v6, 0xbfb8aa3b, v3
	v_exp_f32_e32 v6, v6
	s_nop 0
	v_add_f32_e32 v6, 1.0, v6
	v_rcp_f32_e32 v6, v6
	s_nop 0
	v_mul_f32_e32 v3, v3, v6
	v_or_b32_e32 v6, 25, v2
	v_ashrrev_i32_e32 v7, 31, v6
	v_lshlrev_b64 v[6:7], 11, v[6:7]
	v_cvt_pk_bf16_f32 v3, v3, v161
	v_lshl_add_u64 v[6:7], v[0:1], 0, v[6:7]
	global_store_short v[6:7], v3, off offset:1536
	s_nop 1
	s_waitcnt lgkmcnt(0)
	v_add_f32_dpp v3, v38, v38 quad_perm:[1,0,3,2] row_mask:0xf bank_mask:0xf
	s_nop 1
	s_waitcnt lgkmcnt(0)
	v_add_f32_dpp v3, v3, v3 quad_perm:[2,3,0,1] row_mask:0xf bank_mask:0xf
	s_nop 1
	s_waitcnt lgkmcnt(0)
	v_add_f32_dpp v3, v3, v3 row_half_mirror row_mask:0xf bank_mask:0xf
	s_nop 1
	s_waitcnt lgkmcnt(0)
	v_add_f32_dpp v3, v3, v3 row_mirror row_mask:0xf bank_mask:0xf
	v_mov_b32_e32 v6, v3
	s_nop 0
	s_waitcnt lgkmcnt(0)
	v_permlane16_swap_b32_e32 v3, v6
	v_add_f32_e32 v3, v3, v6
	v_mov_b32_e32 v6, v3
	s_nop 0
	s_waitcnt lgkmcnt(0)
	v_permlane32_swap_b32_e32 v3, v6
	v_add_f32_e32 v3, v3, v6
	v_fmac_f32_e32 v38, 0xbc800000, v3
	v_mul_f32_e32 v3, v38, v38
	s_nop 1
	s_waitcnt lgkmcnt(0)
	v_add_f32_dpp v3, v3, v3 quad_perm:[1,0,3,2] row_mask:0xf bank_mask:0xf
	s_nop 1
	s_waitcnt lgkmcnt(0)
	v_add_f32_dpp v3, v3, v3 quad_perm:[2,3,0,1] row_mask:0xf bank_mask:0xf
	s_nop 1
	s_waitcnt lgkmcnt(0)
	v_add_f32_dpp v3, v3, v3 row_half_mirror row_mask:0xf bank_mask:0xf
	s_nop 1
	s_waitcnt lgkmcnt(0)
	v_add_f32_dpp v3, v3, v3 row_mirror row_mask:0xf bank_mask:0xf
	v_mov_b32_e32 v6, v3
	s_nop 0
	s_waitcnt lgkmcnt(0)
	v_permlane16_swap_b32_e32 v3, v6
	v_add_f32_e32 v3, v3, v6
	v_mov_b32_e32 v6, v3
	s_nop 0
	s_waitcnt lgkmcnt(0)
; __device__ __forceinline__ bf16_t f2bf(float v) { return (bf16_t)(cvt_pk_bf16(v, 0.f) & 0xffffu); }
; __device__ __forceinline__ float sigmoidf_(float v) { return __builtin_amdgcn_rcpf(1.f + __expf(-v)); }
; __device__ __forceinline__ float wave_sum(float v) {
; #pragma unroll
;     for (int o = 1; o < 64; o <<= 1) v += __shfl_xor(v, o);
;     return v;
; }
; __device__ __forceinline__ void conv_item(const Params& p, LAS unsigned char* lds, int l, int item, const bf16_t* UC, bf16_t* MIXA) {
;     ...
; #pragma unroll
;     for (int i = 0; i < 32; ++i) {
;         const float mu = wave_sum(o[i]) * (1.f / 64.f);
;         const float d = o[i] - mu;
;         const float var = wave_sum(d * d) * (1.f / 64.f);
;         const float zn = d * __builtin_amdgcn_rsqf(var + EPSV) * lg + lb;
;         MIXA[(size_t)(rowbase + ts + i) * DM + 768 + ch] = f2bf(zn * sigmoidf_(zn));
;     }
	v_permlane32_swap_b32_e32 v3, v6
	v_add_f32_e32 v3, v3, v6
	v_fmamk_f32 v3, v3, 0x3c800000, v193
	v_rsq_f32_e32 v3, v3
	s_nop 0
	v_mul_f32_e32 v3, v38, v3
	v_fma_f32 v3, v5, v3, v4
	v_mul_f32_e32 v6, 0xbfb8aa3b, v3
	v_exp_f32_e32 v6, v6
	s_nop 0
	v_add_f32_e32 v6, 1.0, v6
	v_rcp_f32_e32 v6, v6
	s_nop 0
	v_mul_f32_e32 v3, v3, v6
	v_or_b32_e32 v6, 26, v2
	v_ashrrev_i32_e32 v7, 31, v6
	v_lshlrev_b64 v[6:7], 11, v[6:7]
	v_cvt_pk_bf16_f32 v3, v3, v161
	v_lshl_add_u64 v[6:7], v[0:1], 0, v[6:7]
	global_store_short v[6:7], v3, off offset:1536
	s_nop 1
	s_waitcnt lgkmcnt(0)
	v_add_f32_dpp v3, v37, v37 quad_perm:[1,0,3,2] row_mask:0xf bank_mask:0xf
	s_nop 1
	s_waitcnt lgkmcnt(0)
	v_add_f32_dpp v3, v3, v3 quad_perm:[2,3,0,1] row_mask:0xf bank_mask:0xf
	s_nop 1
	s_waitcnt lgkmcnt(0)
	v_add_f32_dpp v3, v3, v3 row_half_mirror row_mask:0xf bank_mask:0xf
	s_nop 1
	s_waitcnt lgkmcnt(0)
	v_add_f32_dpp v3, v3, v3 row_mirror row_mask:0xf bank_mask:0xf
	v_mov_b32_e32 v6, v3
	s_nop 0
	s_waitcnt lgkmcnt(0)
	v_permlane16_swap_b32_e32 v3, v6
	v_add_f32_e32 v3, v3, v6
	v_mov_b32_e32 v6, v3
	s_nop 0
	s_waitcnt lgkmcnt(0)
	v_permlane32_swap_b32_e32 v3, v6
	v_add_f32_e32 v3, v3, v6
	v_fmac_f32_e32 v37, 0xbc800000, v3
	v_mul_f32_e32 v3, v37, v37
	s_nop 1
	s_waitcnt lgkmcnt(0)
	v_add_f32_dpp v3, v3, v3 quad_perm:[1,0,3,2] row_mask:0xf bank_mask:0xf
	s_nop 1
	s_waitcnt lgkmcnt(0)
	v_add_f32_dpp v3, v3, v3 quad_perm:[2,3,0,1] row_mask:0xf bank_mask:0xf
	s_nop 1
	s_waitcnt lgkmcnt(0)
	v_add_f32_dpp v3, v3, v3 row_half_mirror row_mask:0xf bank_mask:0xf
	s_nop 1
	s_waitcnt lgkmcnt(0)
	v_add_f32_dpp v3, v3, v3 row_mirror row_mask:0xf bank_mask:0xf
	v_mov_b32_e32 v6, v3
	s_nop 0
	s_waitcnt lgkmcnt(0)
	v_permlane16_swap_b32_e32 v3, v6
	v_add_f32_e32 v3, v3, v6
	v_mov_b32_e32 v6, v3
	s_nop 0
	s_waitcnt lgkmcnt(0)
	v_permlane32_swap_b32_e32 v3, v6
	v_add_f32_e32 v3, v3, v6
	v_fmamk_f32 v3, v3, 0x3c800000, v193
	v_rsq_f32_e32 v3, v3
	s_nop 0
	v_mul_f32_e32 v3, v37, v3
	v_fma_f32 v3, v5, v3, v4
	v_mul_f32_e32 v6, 0xbfb8aa3b, v3
	v_exp_f32_e32 v6, v6
	s_nop 0
	v_add_f32_e32 v6, 1.0, v6
	v_rcp_f32_e32 v6, v6
	s_nop 0
	v_mul_f32_e32 v3, v3, v6
	v_or_b32_e32 v6, 27, v2
	v_ashrrev_i32_e32 v7, 31, v6
	v_lshlrev_b64 v[6:7], 11, v[6:7]
	v_cvt_pk_bf16_f32 v3, v3, v161
	v_lshl_add_u64 v[6:7], v[0:1], 0, v[6:7]
	global_store_short v[6:7], v3, off offset:1536
	s_nop 1
	s_waitcnt lgkmcnt(0)
	v_add_f32_dpp v3, v36, v36 quad_perm:[1,0,3,2] row_mask:0xf bank_mask:0xf
	s_nop 1
	s_waitcnt lgkmcnt(0)
	v_add_f32_dpp v3, v3, v3 quad_perm:[2,3,0,1] row_mask:0xf bank_mask:0xf
	s_nop 1
	s_waitcnt lgkmcnt(0)
	v_add_f32_dpp v3, v3, v3 row_half_mirror row_mask:0xf bank_mask:0xf
	s_nop 1
	s_waitcnt lgkmcnt(0)
	v_add_f32_dpp v3, v3, v3 row_mirror row_mask:0xf bank_mask:0xf
	v_mov_b32_e32 v6, v3
	s_nop 0
	s_waitcnt lgkmcnt(0)
	v_permlane16_swap_b32_e32 v3, v6
	v_add_f32_e32 v3, v3, v6
	v_mov_b32_e32 v6, v3
	s_nop 0
	s_waitcnt lgkmcnt(0)
	v_permlane32_swap_b32_e32 v3, v6
	v_add_f32_e32 v3, v3, v6
	v_fmac_f32_e32 v36, 0xbc800000, v3
	v_mul_f32_e32 v3, v36, v36
	s_nop 1
	s_waitcnt lgkmcnt(0)
	v_add_f32_dpp v3, v3, v3 quad_perm:[1,0,3,2] row_mask:0xf bank_mask:0xf
	s_nop 1
	s_waitcnt lgkmcnt(0)
	v_add_f32_dpp v3, v3, v3 quad_perm:[2,3,0,1] row_mask:0xf bank_mask:0xf
	s_nop 1
	s_waitcnt lgkmcnt(0)
	v_add_f32_dpp v3, v3, v3 row_half_mirror row_mask:0xf bank_mask:0xf
	s_nop 1
	s_waitcnt lgkmcnt(0)
	v_add_f32_dpp v3, v3, v3 row_mirror row_mask:0xf bank_mask:0xf
	v_mov_b32_e32 v6, v3
	s_nop 0
	s_waitcnt lgkmcnt(0)
	v_permlane16_swap_b32_e32 v3, v6
	v_add_f32_e32 v3, v3, v6
	v_mov_b32_e32 v6, v3
	s_nop 0
	s_waitcnt lgkmcnt(0)
	v_permlane32_swap_b32_e32 v3, v6
	v_add_f32_e32 v3, v3, v6
	v_fmamk_f32 v3, v3, 0x3c800000, v193
	v_rsq_f32_e32 v3, v3
	s_nop 0
	v_mul_f32_e32 v3, v36, v3
	v_fma_f32 v3, v5, v3, v4
	v_mul_f32_e32 v6, 0xbfb8aa3b, v3
	v_exp_f32_e32 v6, v6
	s_nop 0
	v_add_f32_e32 v6, 1.0, v6
	v_rcp_f32_e32 v6, v6
	s_nop 0
	v_mul_f32_e32 v3, v3, v6
	v_or_b32_e32 v6, 28, v2
	v_ashrrev_i32_e32 v7, 31, v6
	v_lshlrev_b64 v[6:7], 11, v[6:7]
	v_cvt_pk_bf16_f32 v3, v3, v161
	v_lshl_add_u64 v[6:7], v[0:1], 0, v[6:7]
	global_store_short v[6:7], v3, off offset:1536
	s_nop 1
	s_waitcnt lgkmcnt(0)
	v_add_f32_dpp v3, v34, v34 quad_perm:[1,0,3,2] row_mask:0xf bank_mask:0xf
	s_nop 1
	s_waitcnt lgkmcnt(0)
	v_add_f32_dpp v3, v3, v3 quad_perm:[2,3,0,1] row_mask:0xf bank_mask:0xf
	s_nop 1
	s_waitcnt lgkmcnt(0)
	v_add_f32_dpp v3, v3, v3 row_half_mirror row_mask:0xf bank_mask:0xf
	s_nop 1
	s_waitcnt lgkmcnt(0)
	v_add_f32_dpp v3, v3, v3 row_mirror row_mask:0xf bank_mask:0xf
	v_mov_b32_e32 v6, v3
	s_nop 0
	s_waitcnt lgkmcnt(0)
	v_permlane16_swap_b32_e32 v3, v6
	v_add_f32_e32 v3, v3, v6
	v_mov_b32_e32 v6, v3
	s_nop 0
	s_waitcnt lgkmcnt(0)
	v_permlane32_swap_b32_e32 v3, v6
	v_add_f32_e32 v3, v3, v6
	v_fmac_f32_e32 v34, 0xbc800000, v3
	v_mul_f32_e32 v3, v34, v34
	s_nop 1
	s_waitcnt lgkmcnt(0)
; __device__ __forceinline__ bf16_t f2bf(float v) { return (bf16_t)(cvt_pk_bf16(v, 0.f) & 0xffffu); }
; __device__ __forceinline__ float sigmoidf_(float v) { return __builtin_amdgcn_rcpf(1.f + __expf(-v)); }
; __device__ __forceinline__ float wave_sum(float v) {
; #pragma unroll
;     for (int o = 1; o < 64; o <<= 1) v += __shfl_xor(v, o);
;     return v;
; }
; __device__ __forceinline__ void conv_item(const Params& p, LAS unsigned char* lds, int l, int item, const bf16_t* UC, bf16_t* MIXA) {
;     ...
; #pragma unroll
;     for (int i = 0; i < 32; ++i) {
;         const float mu = wave_sum(o[i]) * (1.f / 64.f);
;         const float d = o[i] - mu;
;         const float var = wave_sum(d * d) * (1.f / 64.f);
;         const float zn = d * __builtin_amdgcn_rsqf(var + EPSV) * lg + lb;
;         MIXA[(size_t)(rowbase + ts + i) * DM + 768 + ch] = f2bf(zn * sigmoidf_(zn));
;     }
;     __syncthreads();
	v_add_f32_dpp v3, v3, v3 quad_perm:[1,0,3,2] row_mask:0xf bank_mask:0xf
	s_nop 1
	s_waitcnt lgkmcnt(0)
	v_add_f32_dpp v3, v3, v3 quad_perm:[2,3,0,1] row_mask:0xf bank_mask:0xf
	s_nop 1
	s_waitcnt lgkmcnt(0)
	v_add_f32_dpp v3, v3, v3 row_half_mirror row_mask:0xf bank_mask:0xf
	s_nop 1
	s_waitcnt lgkmcnt(0)
	v_add_f32_dpp v3, v3, v3 row_mirror row_mask:0xf bank_mask:0xf
	v_mov_b32_e32 v6, v3
	s_nop 0
	s_waitcnt lgkmcnt(0)
	v_permlane16_swap_b32_e32 v3, v6
	v_add_f32_e32 v3, v3, v6
	v_mov_b32_e32 v6, v3
	s_nop 0
	s_waitcnt lgkmcnt(0)
	v_permlane32_swap_b32_e32 v3, v6
	v_add_f32_e32 v3, v3, v6
	v_fmamk_f32 v3, v3, 0x3c800000, v193
	v_rsq_f32_e32 v3, v3
	s_nop 0
	v_mul_f32_e32 v3, v34, v3
	v_fma_f32 v3, v5, v3, v4
	v_mul_f32_e32 v6, 0xbfb8aa3b, v3
	v_exp_f32_e32 v6, v6
	s_nop 0
	v_add_f32_e32 v6, 1.0, v6
	v_rcp_f32_e32 v6, v6
	s_nop 0
	v_mul_f32_e32 v3, v3, v6
	v_or_b32_e32 v6, 29, v2
	v_ashrrev_i32_e32 v7, 31, v6
	v_lshlrev_b64 v[6:7], 11, v[6:7]
	v_cvt_pk_bf16_f32 v3, v3, v161
	v_lshl_add_u64 v[6:7], v[0:1], 0, v[6:7]
	global_store_short v[6:7], v3, off offset:1536
	s_nop 1
	s_waitcnt lgkmcnt(0)
	v_add_f32_dpp v3, v32, v32 quad_perm:[1,0,3,2] row_mask:0xf bank_mask:0xf
	s_nop 1
	s_waitcnt lgkmcnt(0)
	v_add_f32_dpp v3, v3, v3 quad_perm:[2,3,0,1] row_mask:0xf bank_mask:0xf
	s_nop 1
	s_waitcnt lgkmcnt(0)
	v_add_f32_dpp v3, v3, v3 row_half_mirror row_mask:0xf bank_mask:0xf
	s_nop 1
	s_waitcnt lgkmcnt(0)
	v_add_f32_dpp v3, v3, v3 row_mirror row_mask:0xf bank_mask:0xf
	v_mov_b32_e32 v6, v3
	s_nop 0
	s_waitcnt lgkmcnt(0)
	v_permlane16_swap_b32_e32 v3, v6
	v_add_f32_e32 v3, v3, v6
	v_mov_b32_e32 v6, v3
	s_nop 0
	s_waitcnt lgkmcnt(0)
	v_permlane32_swap_b32_e32 v3, v6
	v_add_f32_e32 v3, v3, v6
	v_fmac_f32_e32 v32, 0xbc800000, v3
	v_mul_f32_e32 v3, v32, v32
	s_nop 1
	s_waitcnt lgkmcnt(0)
	v_add_f32_dpp v3, v3, v3 quad_perm:[1,0,3,2] row_mask:0xf bank_mask:0xf
	s_nop 1
	s_waitcnt lgkmcnt(0)
	v_add_f32_dpp v3, v3, v3 quad_perm:[2,3,0,1] row_mask:0xf bank_mask:0xf
	s_nop 1
	s_waitcnt lgkmcnt(0)
	v_add_f32_dpp v3, v3, v3 row_half_mirror row_mask:0xf bank_mask:0xf
	s_nop 1
	s_waitcnt lgkmcnt(0)
	v_add_f32_dpp v3, v3, v3 row_mirror row_mask:0xf bank_mask:0xf
	v_mov_b32_e32 v6, v3
	s_nop 0
	s_waitcnt lgkmcnt(0)
	v_permlane16_swap_b32_e32 v3, v6
	v_add_f32_e32 v3, v3, v6
	v_mov_b32_e32 v6, v3
	s_nop 0
	s_waitcnt lgkmcnt(0)
	v_permlane32_swap_b32_e32 v3, v6
	v_add_f32_e32 v3, v3, v6
	v_fmamk_f32 v3, v3, 0x3c800000, v193
	v_rsq_f32_e32 v3, v3
	s_nop 0
	v_mul_f32_e32 v3, v32, v3
	v_fma_f32 v3, v5, v3, v4
	v_mul_f32_e32 v6, 0xbfb8aa3b, v3
	v_exp_f32_e32 v6, v6
	s_nop 0
	v_add_f32_e32 v6, 1.0, v6
	v_rcp_f32_e32 v6, v6
	s_nop 0
	v_mul_f32_e32 v3, v3, v6
	v_or_b32_e32 v6, 30, v2
	v_ashrrev_i32_e32 v7, 31, v6
	v_lshlrev_b64 v[6:7], 11, v[6:7]
	v_cvt_pk_bf16_f32 v3, v3, v161
	v_lshl_add_u64 v[6:7], v[0:1], 0, v[6:7]
	global_store_short v[6:7], v3, off offset:1536
	s_nop 1
	v_or_b32_e32 v2, 31, v2
	s_waitcnt lgkmcnt(0)
	v_add_f32_dpp v3, v60, v60 quad_perm:[1,0,3,2] row_mask:0xf bank_mask:0xf
	s_nop 1
	s_waitcnt lgkmcnt(0)
	v_add_f32_dpp v3, v3, v3 quad_perm:[2,3,0,1] row_mask:0xf bank_mask:0xf
	s_nop 1
	s_waitcnt lgkmcnt(0)
	v_add_f32_dpp v3, v3, v3 row_half_mirror row_mask:0xf bank_mask:0xf
	s_nop 1
	s_waitcnt lgkmcnt(0)
	v_add_f32_dpp v3, v3, v3 row_mirror row_mask:0xf bank_mask:0xf
	v_mov_b32_e32 v6, v3
	s_nop 0
	s_waitcnt lgkmcnt(0)
	v_permlane16_swap_b32_e32 v3, v6
	v_add_f32_e32 v3, v3, v6
	v_mov_b32_e32 v6, v3
	s_nop 0
	s_waitcnt lgkmcnt(0)
	v_permlane32_swap_b32_e32 v3, v6
	v_add_f32_e32 v3, v3, v6
	v_fmac_f32_e32 v60, 0xbc800000, v3
	v_mul_f32_e32 v3, v60, v60
	s_nop 1
	s_waitcnt lgkmcnt(0)
	v_add_f32_dpp v3, v3, v3 quad_perm:[1,0,3,2] row_mask:0xf bank_mask:0xf
	s_nop 1
	s_waitcnt lgkmcnt(0)
	v_add_f32_dpp v3, v3, v3 quad_perm:[2,3,0,1] row_mask:0xf bank_mask:0xf
	s_nop 1
	s_waitcnt lgkmcnt(0)
	v_add_f32_dpp v3, v3, v3 row_half_mirror row_mask:0xf bank_mask:0xf
	s_nop 1
	s_waitcnt lgkmcnt(0)
	v_add_f32_dpp v3, v3, v3 row_mirror row_mask:0xf bank_mask:0xf
	v_mov_b32_e32 v6, v3
	s_nop 0
	s_waitcnt lgkmcnt(0)
	v_permlane16_swap_b32_e32 v3, v6
	v_add_f32_e32 v3, v3, v6
	v_mov_b32_e32 v6, v3
	s_nop 0
	s_waitcnt lgkmcnt(0)
	v_permlane32_swap_b32_e32 v3, v6
	v_add_f32_e32 v3, v3, v6
	v_fmamk_f32 v3, v3, 0x3c800000, v193
	v_rsq_f32_e32 v3, v3
	s_nop 0
	v_mul_f32_e32 v3, v60, v3
	v_fmac_f32_e32 v4, v5, v3
	v_mul_f32_e32 v3, 0xbfb8aa3b, v4
	v_exp_f32_e32 v3, v3
	s_nop 0
	v_add_f32_e32 v3, 1.0, v3
	v_rcp_f32_e32 v3, v3
	s_nop 0
	v_mul_f32_e32 v3, v4, v3
	v_cvt_pk_bf16_f32 v4, v3, v161
	v_ashrrev_i32_e32 v3, 31, v2
	v_lshlrev_b64 v[2:3], 11, v[2:3]
	v_lshl_add_u64 v[0:1], v[0:1], 0, v[2:3]
	global_store_short v[0:1], v4, off offset:1536
	s_barrier
	s_cbranch_scc1 .LBB0_751

; __global__ void __launch_bounds__(512, 2) fwd_kernel(Params p) {
	.amdhsa_kernel _Z10fwd_kernel6Params
		.amdhsa_group_segment_fixed_size 0
		.amdhsa_private_segment_fixed_size 0
		.amdhsa_kernarg_size 472
		.amdhsa_user_sgpr_count 2
		.amdhsa_user_sgpr_dispatch_ptr 0
		.amdhsa_user_sgpr_queue_ptr 0
		.amdhsa_user_sgpr_kernarg_segment_ptr 1
		.amdhsa_user_sgpr_dispatch_id 0
		.amdhsa_user_sgpr_kernarg_preload_length 0
		.amdhsa_user_sgpr_kernarg_preload_offset 0
		.amdhsa_user_sgpr_private_segment_size 0
		.amdhsa_uses_dynamic_stack 0
		.amdhsa_enable_private_segment 0
		.amdhsa_system_sgpr_workgroup_id_x 1
		.amdhsa_system_sgpr_workgroup_id_y 0
		.amdhsa_system_sgpr_workgroup_id_z 0
		.amdhsa_system_sgpr_workgroup_info 0
		.amdhsa_system_vgpr_workitem_id 2
		.amdhsa_next_free_vgpr 256
		.amdhsa_next_free_sgpr 102
		.amdhsa_accum_offset 256
		.amdhsa_reserve_vcc 1
		.amdhsa_float_round_mode_32 0
		.amdhsa_float_round_mode_16_64 0
		.amdhsa_float_denorm_mode_32 3
		.amdhsa_float_denorm_mode_16_64 3
		.amdhsa_dx10_clamp 1
		.amdhsa_ieee_mode 1
		.amdhsa_fp16_overflow 0
		.amdhsa_tg_split 0
		.amdhsa_exception_fp_ieee_invalid_op 0
		.amdhsa_exception_fp_denorm_src 0
		.amdhsa_exception_fp_ieee_div_zero 0
		.amdhsa_exception_fp_ieee_overflow 0
		.amdhsa_exception_fp_ieee_underflow 0
		.amdhsa_exception_fp_ieee_inexact 0
		.amdhsa_exception_int_div_zero 0
	.end_amdhsa_kernel

; __global__ void __launch_bounds__(512, 2) fwd_kernel(Params p) {
amdhsa.kernels:
  - .agpr_count:     0
    .args:
      - .offset:         0
        .size:           216
        .value_kind:     by_value
      - .offset:         216
        .size:           4
        .value_kind:     hidden_block_count_x
      - .offset:         220
        .size:           4
        .value_kind:     hidden_block_count_y
      - .offset:         224
        .size:           4
        .value_kind:     hidden_block_count_z
      - .offset:         228
        .size:           2
        .value_kind:     hidden_group_size_x
      - .offset:         230
        .size:           2
        .value_kind:     hidden_group_size_y
      - .offset:         232
        .size:           2
        .value_kind:     hidden_group_size_z
      - .offset:         234
        .size:           2
        .value_kind:     hidden_remainder_x
      - .offset:         236
        .size:           2
        .value_kind:     hidden_remainder_y
      - .offset:         238
        .size:           2
        .value_kind:     hidden_remainder_z
      - .offset:         256
        .size:           8
        .value_kind:     hidden_global_offset_x
      - .offset:         264
        .size:           8
        .value_kind:     hidden_global_offset_y
      - .offset:         272
        .size:           8
        .value_kind:     hidden_global_offset_z
      - .offset:         280
        .size:           2
        .value_kind:     hidden_grid_dims
      - .offset:         304
        .size:           8
        .value_kind:     hidden_multigrid_sync_arg
      - .offset:         336
        .size:           4
        .value_kind:     hidden_dynamic_lds_size
    .group_segment_fixed_size: 0
    .kernarg_segment_align: 8
    .kernarg_segment_size: 472
    .language:       OpenCL C
    .language_version:
      - 2
      - 0
    .max_flat_workgroup_size: 512
    .name:           _Z10fwd_kernel6Params
    .private_segment_fixed_size: 0
    .sgpr_count:     108
    .sgpr_spill_count: 248
    .symbol:         _Z10fwd_kernel6Params.kd
    .uniform_work_group_size: 1
    .uses_dynamic_stack: false
    .vgpr_count:     256
    .vgpr_spill_count: 0
    .wavefront_size: 64
